# team-local activations (XN/XB, Y, x1b/XN2, ACT) stored write-back instead of write-through under the verified placement; L2 write-back added to the barriers' fallback path
# speedup vs baseline: 1.0240x; 1.0017x over previous
.Lp1_nw0:
	v_pk_mul_f32 v[90:91], v[116:117], v[116:117]
	v_pk_mul_f32 v[92:93], v[114:115], v[114:115]
	v_pk_mul_f32 v[100:101], v[120:121], v[120:121]
	v_pk_mul_f32 v[102:103], v[118:119], v[118:119]
	v_pk_mov_b32 v[108:109], v[92:93], v[90:91] op_sel:[1,0]
	v_mov_b32_e32 v93, v91
	v_pk_mov_b32 v[90:91], v[102:103], v[100:101] op_sel:[1,0]
	v_mov_b32_e32 v103, v101
	v_mul_f32_e32 v107, v129, v129
	v_mul_f32_e32 v104, v123, v123
	v_mul_f32_e32 v106, v125, v125
	v_pk_add_f32 v[92:93], v[108:109], v[92:93]
	v_pk_add_f32 v[90:91], v[90:91], v[102:103]
	v_mul_f32_e32 v89, v128, v128
	v_mul_f32_e32 v110, v126, v126
	v_mul_f32_e32 v111, v127, v127
	v_pk_fma_f32 v[100:101], v[122:123], v[122:123], v[104:105] op_sel_hi:[1,1,0]
	v_pk_fma_f32 v[104:105], v[124:125], v[124:125], v[106:107] op_sel_hi:[1,1,0]
	v_pk_add_f32 v[92:93], v[92:93], v[92:93] op_sel:[0,1] op_sel_hi:[1,0]
	v_pk_add_f32 v[90:91], v[90:91], v[90:91] op_sel:[0,1] op_sel_hi:[1,0]
	v_mov_b32_e32 v101, v89
	v_mov_b32_e32 v105, v107
	v_mov_b32_e32 v93, v110
	v_mov_b32_e32 v91, v111
	v_pk_add_f32 v[100:101], v[100:101], v[104:105]
	v_pk_add_f32 v[90:91], v[92:93], v[90:91]
	s_nop 0
	v_pk_add_f32 v[90:91], v[90:91], v[100:101]
	s_nop 0
	v_add_f32_e32 v89, v90, v91
	s_nop 1
	v_add_f32_dpp v89, v89, v89 quad_perm:[1,0,3,2] row_mask:0xf bank_mask:0xf bound_ctrl:1
	s_nop 1
	v_add_f32_dpp v89, v89, v89 quad_perm:[2,3,0,1] row_mask:0xf bank_mask:0xf bound_ctrl:1
	s_nop 1
	v_add_f32_dpp v89, v89, v89 row_half_mirror row_mask:0xf bank_mask:0xf bound_ctrl:1
	s_nop 1
	v_add_f32_dpp v89, v89, v89 row_mirror row_mask:0xf bank_mask:0xf bound_ctrl:1
	s_nop 0
	v_readlane_b32 s0, v89, 16
	v_readlane_b32 s28, v89, 48
	v_readlane_b32 s26, v89, 0
	v_readlane_b32 s27, v89, 32
	v_mov_b32_e32 v90, s0
	v_mov_b32_e32 v91, s28
	v_pk_add_f32 v[90:91], s[26:27], v[90:91]
	s_nop 0
	v_add_f32_e32 v89, v90, v91
	v_fmamk_f32 v89, v89, 0x3a800000, v88
	v_rsq_f32_e32 v72, v89
	v_cvt_pk_bf16_f32 v34, v114, v115
	v_cvt_pk_bf16_f32 v35, v116, v117
	v_cvt_pk_bf16_f32 v36, v118, v119
	v_cvt_pk_bf16_f32 v37, v120, v121
	v_lshl_add_u64 v[70:71], v[64:65], 0, s[46:47]
	global_store_dwordx4 v[64:65], v[34:37], off
	s_nop 1
	v_cvt_pk_bf16_f32 v34, v122, v123
	v_cvt_pk_bf16_f32 v35, v124, v125
	v_cvt_pk_bf16_f32 v36, v126, v127
	v_cvt_pk_bf16_f32 v37, v128, v129
	s_nop 0
	global_store_dwordx4 v[70:71], v[34:37], off
	s_nop 1
	v_lshl_add_u64 v[64:65], v[64:65], 0, s[76:77]
	s_cmp_eq_u32 s97, 1
	s_cbranch_scc1 .Lp1_nw1
	s_waitcnt vmcnt(26)
.Lp1_nw1:
	v_pk_mul_f32 v[90:91], v[132:133], v[132:133]
	v_pk_mul_f32 v[92:93], v[130:131], v[130:131]
	v_pk_mul_f32 v[100:101], v[136:137], v[136:137]
	v_pk_mul_f32 v[102:103], v[134:135], v[134:135]
	v_pk_mov_b32 v[108:109], v[92:93], v[90:91] op_sel:[1,0]
	v_mov_b32_e32 v93, v91
	v_pk_mov_b32 v[90:91], v[102:103], v[100:101] op_sel:[1,0]
	v_mov_b32_e32 v103, v101
	v_mul_f32_e32 v107, v145, v145
	v_mul_f32_e32 v104, v139, v139
	v_mul_f32_e32 v106, v141, v141
	v_pk_add_f32 v[92:93], v[108:109], v[92:93]
	v_pk_add_f32 v[90:91], v[90:91], v[102:103]
	v_mul_f32_e32 v89, v144, v144
	v_mul_f32_e32 v110, v142, v142
	v_mul_f32_e32 v111, v143, v143
	v_pk_fma_f32 v[100:101], v[138:139], v[138:139], v[104:105] op_sel_hi:[1,1,0]
	v_pk_fma_f32 v[104:105], v[140:141], v[140:141], v[106:107] op_sel_hi:[1,1,0]
	v_pk_add_f32 v[92:93], v[92:93], v[92:93] op_sel:[0,1] op_sel_hi:[1,0]
	v_pk_add_f32 v[90:91], v[90:91], v[90:91] op_sel:[0,1] op_sel_hi:[1,0]
	v_mov_b32_e32 v101, v89
	v_mov_b32_e32 v105, v107
	v_mov_b32_e32 v93, v110
	v_mov_b32_e32 v91, v111
	v_pk_add_f32 v[100:101], v[100:101], v[104:105]
	v_pk_add_f32 v[90:91], v[92:93], v[90:91]
	s_nop 0
	v_pk_add_f32 v[90:91], v[90:91], v[100:101]
	s_nop 0
	v_add_f32_e32 v89, v90, v91
	s_nop 1
	v_add_f32_dpp v89, v89, v89 quad_perm:[1,0,3,2] row_mask:0xf bank_mask:0xf bound_ctrl:1
	s_nop 1
	v_add_f32_dpp v89, v89, v89 quad_perm:[2,3,0,1] row_mask:0xf bank_mask:0xf bound_ctrl:1
	s_nop 1
	v_add_f32_dpp v89, v89, v89 row_half_mirror row_mask:0xf bank_mask:0xf bound_ctrl:1
	s_nop 1
	v_add_f32_dpp v89, v89, v89 row_mirror row_mask:0xf bank_mask:0xf bound_ctrl:1
	s_nop 0
	v_readlane_b32 s0, v89, 16
	v_readlane_b32 s28, v89, 48
	v_readlane_b32 s26, v89, 0
	v_readlane_b32 s27, v89, 32
	v_mov_b32_e32 v90, s0
	v_mov_b32_e32 v91, s28
	v_pk_add_f32 v[90:91], s[26:27], v[90:91]
	s_nop 0
	v_add_f32_e32 v89, v90, v91
	v_fmamk_f32 v89, v89, 0x3a800000, v88
	v_rsq_f32_e32 v73, v89
	v_cvt_pk_bf16_f32 v34, v130, v131
	v_cvt_pk_bf16_f32 v35, v132, v133
	v_cvt_pk_bf16_f32 v36, v134, v135
	v_cvt_pk_bf16_f32 v37, v136, v137
	v_lshl_add_u64 v[70:71], v[64:65], 0, s[46:47]
	global_store_dwordx4 v[64:65], v[34:37], off
	s_nop 1
	v_cvt_pk_bf16_f32 v34, v138, v139
	v_cvt_pk_bf16_f32 v35, v140, v141
	v_cvt_pk_bf16_f32 v36, v142, v143
	v_cvt_pk_bf16_f32 v37, v144, v145
	s_nop 0
	global_store_dwordx4 v[70:71], v[34:37], off
	s_nop 1
	v_lshl_add_u64 v[64:65], v[64:65], 0, s[76:77]
	s_cmp_eq_u32 s97, 1
	s_cbranch_scc1 .Lp1_nw2
	s_waitcnt vmcnt(24)
.Lp1_nw2:
	v_pk_mul_f32 v[90:91], v[148:149], v[148:149]
	v_pk_mul_f32 v[92:93], v[146:147], v[146:147]
	v_pk_mul_f32 v[100:101], v[152:153], v[152:153]
	v_pk_mul_f32 v[102:103], v[150:151], v[150:151]
	v_pk_mov_b32 v[108:109], v[92:93], v[90:91] op_sel:[1,0]
	v_mov_b32_e32 v93, v91
	v_pk_mov_b32 v[90:91], v[102:103], v[100:101] op_sel:[1,0]
	v_mov_b32_e32 v103, v101
	v_mul_f32_e32 v107, v161, v161
	v_mul_f32_e32 v104, v155, v155
	v_mul_f32_e32 v106, v157, v157
	v_pk_add_f32 v[92:93], v[108:109], v[92:93]
	v_pk_add_f32 v[90:91], v[90:91], v[102:103]
	v_mul_f32_e32 v89, v160, v160
	v_mul_f32_e32 v110, v158, v158
	v_mul_f32_e32 v111, v159, v159
	v_pk_fma_f32 v[100:101], v[154:155], v[154:155], v[104:105] op_sel_hi:[1,1,0]
	v_pk_fma_f32 v[104:105], v[156:157], v[156:157], v[106:107] op_sel_hi:[1,1,0]
	v_pk_add_f32 v[92:93], v[92:93], v[92:93] op_sel:[0,1] op_sel_hi:[1,0]
	v_pk_add_f32 v[90:91], v[90:91], v[90:91] op_sel:[0,1] op_sel_hi:[1,0]
	v_mov_b32_e32 v101, v89
	v_mov_b32_e32 v105, v107
	v_mov_b32_e32 v93, v110
	v_mov_b32_e32 v91, v111
	v_pk_add_f32 v[100:101], v[100:101], v[104:105]
	v_pk_add_f32 v[90:91], v[92:93], v[90:91]
	s_nop 0
	v_pk_add_f32 v[90:91], v[90:91], v[100:101]
	s_nop 0
	v_add_f32_e32 v89, v90, v91
	s_nop 1
	v_add_f32_dpp v89, v89, v89 quad_perm:[1,0,3,2] row_mask:0xf bank_mask:0xf bound_ctrl:1
	s_nop 1
	v_add_f32_dpp v89, v89, v89 quad_perm:[2,3,0,1] row_mask:0xf bank_mask:0xf bound_ctrl:1
	s_nop 1
	v_add_f32_dpp v89, v89, v89 row_half_mirror row_mask:0xf bank_mask:0xf bound_ctrl:1
	s_nop 1
	v_add_f32_dpp v89, v89, v89 row_mirror row_mask:0xf bank_mask:0xf bound_ctrl:1
	s_nop 0
	v_readlane_b32 s0, v89, 16
	v_readlane_b32 s28, v89, 48
	v_readlane_b32 s26, v89, 0
	v_readlane_b32 s27, v89, 32
	v_mov_b32_e32 v90, s0
	v_mov_b32_e32 v91, s28
	v_pk_add_f32 v[90:91], s[26:27], v[90:91]
	s_nop 0
	v_add_f32_e32 v89, v90, v91
	v_fmamk_f32 v89, v89, 0x3a800000, v88
	v_rsq_f32_e32 v74, v89
	v_cvt_pk_bf16_f32 v34, v146, v147
	v_cvt_pk_bf16_f32 v35, v148, v149
	v_cvt_pk_bf16_f32 v36, v150, v151
	v_cvt_pk_bf16_f32 v37, v152, v153
	v_lshl_add_u64 v[70:71], v[64:65], 0, s[46:47]
	global_store_dwordx4 v[64:65], v[34:37], off
	s_nop 1
	v_cvt_pk_bf16_f32 v34, v154, v155
	v_cvt_pk_bf16_f32 v35, v156, v157
	v_cvt_pk_bf16_f32 v36, v158, v159
	v_cvt_pk_bf16_f32 v37, v160, v161
	s_nop 0
	global_store_dwordx4 v[70:71], v[34:37], off
	s_nop 1
	v_lshl_add_u64 v[64:65], v[64:65], 0, s[76:77]
	s_cmp_eq_u32 s97, 1
	s_cbranch_scc1 .Lp1_nw3
	s_waitcnt vmcnt(22)
.Lp1_nw3:
	v_pk_mul_f32 v[90:91], v[164:165], v[164:165]
	v_pk_mul_f32 v[92:93], v[162:163], v[162:163]
	v_pk_mul_f32 v[100:101], v[168:169], v[168:169]
	v_pk_mul_f32 v[102:103], v[166:167], v[166:167]
	v_pk_mov_b32 v[108:109], v[92:93], v[90:91] op_sel:[1,0]
	v_mov_b32_e32 v93, v91
	v_pk_mov_b32 v[90:91], v[102:103], v[100:101] op_sel:[1,0]
	v_mov_b32_e32 v103, v101
	v_mul_f32_e32 v107, v177, v177
	v_mul_f32_e32 v104, v171, v171
	v_mul_f32_e32 v106, v173, v173
	v_pk_add_f32 v[92:93], v[108:109], v[92:93]
	v_pk_add_f32 v[90:91], v[90:91], v[102:103]
	v_mul_f32_e32 v89, v176, v176
	v_mul_f32_e32 v110, v174, v174
	v_mul_f32_e32 v111, v175, v175
	v_pk_fma_f32 v[100:101], v[170:171], v[170:171], v[104:105] op_sel_hi:[1,1,0]
	v_pk_fma_f32 v[104:105], v[172:173], v[172:173], v[106:107] op_sel_hi:[1,1,0]
	v_pk_add_f32 v[92:93], v[92:93], v[92:93] op_sel:[0,1] op_sel_hi:[1,0]
	v_pk_add_f32 v[90:91], v[90:91], v[90:91] op_sel:[0,1] op_sel_hi:[1,0]
	v_mov_b32_e32 v101, v89
	v_mov_b32_e32 v105, v107
	v_mov_b32_e32 v93, v110
	v_mov_b32_e32 v91, v111
	v_pk_add_f32 v[100:101], v[100:101], v[104:105]
	v_pk_add_f32 v[90:91], v[92:93], v[90:91]
	s_nop 0
	v_pk_add_f32 v[90:91], v[90:91], v[100:101]
	s_nop 0
	v_add_f32_e32 v89, v90, v91
	s_nop 1
	v_add_f32_dpp v89, v89, v89 quad_perm:[1,0,3,2] row_mask:0xf bank_mask:0xf bound_ctrl:1
	s_nop 1
	v_add_f32_dpp v89, v89, v89 quad_perm:[2,3,0,1] row_mask:0xf bank_mask:0xf bound_ctrl:1
	s_nop 1
	v_add_f32_dpp v89, v89, v89 row_half_mirror row_mask:0xf bank_mask:0xf bound_ctrl:1
	s_nop 1
	v_add_f32_dpp v89, v89, v89 row_mirror row_mask:0xf bank_mask:0xf bound_ctrl:1
	s_nop 0
	v_readlane_b32 s0, v89, 16
	v_readlane_b32 s28, v89, 48
	v_readlane_b32 s26, v89, 0
	v_readlane_b32 s27, v89, 32
	v_mov_b32_e32 v90, s0
	v_mov_b32_e32 v91, s28
	v_pk_add_f32 v[90:91], s[26:27], v[90:91]
	s_nop 0
	v_add_f32_e32 v89, v90, v91
	v_fmamk_f32 v89, v89, 0x3a800000, v88
	v_rsq_f32_e32 v75, v89
	v_cvt_pk_bf16_f32 v34, v162, v163
	v_cvt_pk_bf16_f32 v35, v164, v165
	v_cvt_pk_bf16_f32 v36, v166, v167
	v_cvt_pk_bf16_f32 v37, v168, v169
	v_lshl_add_u64 v[70:71], v[64:65], 0, s[46:47]
	global_store_dwordx4 v[64:65], v[34:37], off
	s_nop 1
	v_cvt_pk_bf16_f32 v34, v170, v171
	v_cvt_pk_bf16_f32 v35, v172, v173
	v_cvt_pk_bf16_f32 v36, v174, v175
	v_cvt_pk_bf16_f32 v37, v176, v177
	s_nop 0
	global_store_dwordx4 v[70:71], v[34:37], off
	s_nop 1
	v_lshl_add_u64 v[64:65], v[64:65], 0, s[76:77]
	s_cmp_eq_u32 s97, 1
	s_cbranch_scc1 .Lp1_nw4
	s_waitcnt vmcnt(20)
.Lp1_nw4:
	v_pk_mul_f32 v[90:91], v[180:181], v[180:181]
	v_pk_mul_f32 v[92:93], v[178:179], v[178:179]
	v_pk_mul_f32 v[100:101], v[184:185], v[184:185]
	v_pk_mul_f32 v[102:103], v[182:183], v[182:183]
	v_pk_mov_b32 v[108:109], v[92:93], v[90:91] op_sel:[1,0]
	v_mov_b32_e32 v93, v91
	v_pk_mov_b32 v[90:91], v[102:103], v[100:101] op_sel:[1,0]
	v_mov_b32_e32 v103, v101
	v_mul_f32_e32 v107, v193, v193
	v_mul_f32_e32 v104, v187, v187
	v_mul_f32_e32 v106, v189, v189
	v_pk_add_f32 v[92:93], v[108:109], v[92:93]
	v_pk_add_f32 v[90:91], v[90:91], v[102:103]
	v_mul_f32_e32 v89, v192, v192
	v_mul_f32_e32 v110, v190, v190
	v_mul_f32_e32 v111, v191, v191
	v_pk_fma_f32 v[100:101], v[186:187], v[186:187], v[104:105] op_sel_hi:[1,1,0]
	v_pk_fma_f32 v[104:105], v[188:189], v[188:189], v[106:107] op_sel_hi:[1,1,0]
	v_pk_add_f32 v[92:93], v[92:93], v[92:93] op_sel:[0,1] op_sel_hi:[1,0]
	v_pk_add_f32 v[90:91], v[90:91], v[90:91] op_sel:[0,1] op_sel_hi:[1,0]
	v_mov_b32_e32 v101, v89
	v_mov_b32_e32 v105, v107
	v_mov_b32_e32 v93, v110
	v_mov_b32_e32 v91, v111
	v_pk_add_f32 v[100:101], v[100:101], v[104:105]
	v_pk_add_f32 v[90:91], v[92:93], v[90:91]
	s_nop 0
	v_pk_add_f32 v[90:91], v[90:91], v[100:101]
	s_nop 0
	v_add_f32_e32 v89, v90, v91
	s_nop 1
	v_add_f32_dpp v89, v89, v89 quad_perm:[1,0,3,2] row_mask:0xf bank_mask:0xf bound_ctrl:1
	s_nop 1
	v_add_f32_dpp v89, v89, v89 quad_perm:[2,3,0,1] row_mask:0xf bank_mask:0xf bound_ctrl:1
	s_nop 1
	v_add_f32_dpp v89, v89, v89 row_half_mirror row_mask:0xf bank_mask:0xf bound_ctrl:1
	s_nop 1
	v_add_f32_dpp v89, v89, v89 row_mirror row_mask:0xf bank_mask:0xf bound_ctrl:1
	s_nop 0
	v_readlane_b32 s0, v89, 16
	v_readlane_b32 s28, v89, 48
	v_readlane_b32 s26, v89, 0
	v_readlane_b32 s27, v89, 32
	v_mov_b32_e32 v90, s0
	v_mov_b32_e32 v91, s28
	v_pk_add_f32 v[90:91], s[26:27], v[90:91]
	s_nop 0
	v_add_f32_e32 v89, v90, v91
	v_fmamk_f32 v89, v89, 0x3a800000, v88
	v_rsq_f32_e32 v76, v89
	v_cvt_pk_bf16_f32 v34, v178, v179
	v_cvt_pk_bf16_f32 v35, v180, v181
	v_cvt_pk_bf16_f32 v36, v182, v183
	v_cvt_pk_bf16_f32 v37, v184, v185
	v_lshl_add_u64 v[70:71], v[64:65], 0, s[46:47]
	global_store_dwordx4 v[64:65], v[34:37], off
	s_nop 1
	v_cvt_pk_bf16_f32 v34, v186, v187
	v_cvt_pk_bf16_f32 v35, v188, v189
	v_cvt_pk_bf16_f32 v36, v190, v191
	v_cvt_pk_bf16_f32 v37, v192, v193
	s_nop 0
	global_store_dwordx4 v[70:71], v[34:37], off
	s_nop 1
	v_lshl_add_u64 v[64:65], v[64:65], 0, s[76:77]
	s_cmp_eq_u32 s97, 1
	s_cbranch_scc1 .Lp1_nw5
	s_waitcnt vmcnt(18)
.Lp1_nw5:
	v_pk_mul_f32 v[90:91], v[196:197], v[196:197]
	v_pk_mul_f32 v[92:93], v[194:195], v[194:195]
	v_pk_mul_f32 v[100:101], v[200:201], v[200:201]
	v_pk_mul_f32 v[102:103], v[198:199], v[198:199]
	v_pk_mov_b32 v[108:109], v[92:93], v[90:91] op_sel:[1,0]
	v_mov_b32_e32 v93, v91
	v_pk_mov_b32 v[90:91], v[102:103], v[100:101] op_sel:[1,0]
	v_mov_b32_e32 v103, v101
	v_mul_f32_e32 v107, v209, v209
	v_mul_f32_e32 v104, v203, v203
	v_mul_f32_e32 v106, v205, v205
	v_pk_add_f32 v[92:93], v[108:109], v[92:93]
	v_pk_add_f32 v[90:91], v[90:91], v[102:103]
	v_mul_f32_e32 v89, v208, v208
	v_mul_f32_e32 v110, v206, v206
	v_mul_f32_e32 v111, v207, v207
	v_pk_fma_f32 v[100:101], v[202:203], v[202:203], v[104:105] op_sel_hi:[1,1,0]
	v_pk_fma_f32 v[104:105], v[204:205], v[204:205], v[106:107] op_sel_hi:[1,1,0]
	v_pk_add_f32 v[92:93], v[92:93], v[92:93] op_sel:[0,1] op_sel_hi:[1,0]
	v_pk_add_f32 v[90:91], v[90:91], v[90:91] op_sel:[0,1] op_sel_hi:[1,0]
	v_mov_b32_e32 v101, v89
	v_mov_b32_e32 v105, v107
	v_mov_b32_e32 v93, v110
	v_mov_b32_e32 v91, v111
	v_pk_add_f32 v[100:101], v[100:101], v[104:105]
	v_pk_add_f32 v[90:91], v[92:93], v[90:91]
	s_nop 0
	v_pk_add_f32 v[90:91], v[90:91], v[100:101]
	s_nop 0
	v_add_f32_e32 v89, v90, v91
	s_nop 1
	v_add_f32_dpp v89, v89, v89 quad_perm:[1,0,3,2] row_mask:0xf bank_mask:0xf bound_ctrl:1
	s_nop 1
	v_add_f32_dpp v89, v89, v89 quad_perm:[2,3,0,1] row_mask:0xf bank_mask:0xf bound_ctrl:1
	s_nop 1
	v_add_f32_dpp v89, v89, v89 row_half_mirror row_mask:0xf bank_mask:0xf bound_ctrl:1
	s_nop 1
	v_add_f32_dpp v89, v89, v89 row_mirror row_mask:0xf bank_mask:0xf bound_ctrl:1
	s_nop 0
	v_readlane_b32 s0, v89, 16
	v_readlane_b32 s28, v89, 48
	v_readlane_b32 s26, v89, 0
	v_readlane_b32 s27, v89, 32
	v_mov_b32_e32 v90, s0
	v_mov_b32_e32 v91, s28
	v_pk_add_f32 v[90:91], s[26:27], v[90:91]
	s_nop 0
	v_add_f32_e32 v89, v90, v91
	v_fmamk_f32 v89, v89, 0x3a800000, v88
	v_rsq_f32_e32 v77, v89
	v_cvt_pk_bf16_f32 v34, v194, v195
	v_cvt_pk_bf16_f32 v35, v196, v197
	v_cvt_pk_bf16_f32 v36, v198, v199
	v_cvt_pk_bf16_f32 v37, v200, v201
	v_lshl_add_u64 v[70:71], v[64:65], 0, s[46:47]
	global_store_dwordx4 v[64:65], v[34:37], off
	s_nop 1
	v_cvt_pk_bf16_f32 v34, v202, v203
	v_cvt_pk_bf16_f32 v35, v204, v205
	v_cvt_pk_bf16_f32 v36, v206, v207
	v_cvt_pk_bf16_f32 v37, v208, v209
	s_nop 0
	global_store_dwordx4 v[70:71], v[34:37], off
	s_nop 1
	v_lshl_add_u64 v[64:65], v[64:65], 0, s[76:77]
	s_cmp_eq_u32 s97, 1
	s_cbranch_scc1 .Lp1_nw6
	s_waitcnt vmcnt(16)
.Lp1_nw6:
	v_pk_mul_f32 v[90:91], v[212:213], v[212:213]
	v_pk_mul_f32 v[92:93], v[210:211], v[210:211]
	v_pk_mul_f32 v[100:101], v[216:217], v[216:217]
	v_pk_mul_f32 v[102:103], v[214:215], v[214:215]
	v_pk_mov_b32 v[108:109], v[92:93], v[90:91] op_sel:[1,0]
	v_mov_b32_e32 v93, v91
	v_pk_mov_b32 v[90:91], v[102:103], v[100:101] op_sel:[1,0]
	v_mov_b32_e32 v103, v101
	v_mul_f32_e32 v107, v225, v225
	v_mul_f32_e32 v104, v219, v219
	v_mul_f32_e32 v106, v221, v221
	v_pk_add_f32 v[92:93], v[108:109], v[92:93]
	v_pk_add_f32 v[90:91], v[90:91], v[102:103]
	v_mul_f32_e32 v89, v224, v224
	v_mul_f32_e32 v110, v222, v222
	v_mul_f32_e32 v111, v223, v223
	v_pk_fma_f32 v[100:101], v[218:219], v[218:219], v[104:105] op_sel_hi:[1,1,0]
	v_pk_fma_f32 v[104:105], v[220:221], v[220:221], v[106:107] op_sel_hi:[1,1,0]
	v_pk_add_f32 v[92:93], v[92:93], v[92:93] op_sel:[0,1] op_sel_hi:[1,0]
	v_pk_add_f32 v[90:91], v[90:91], v[90:91] op_sel:[0,1] op_sel_hi:[1,0]
	v_mov_b32_e32 v101, v89
	v_mov_b32_e32 v105, v107
	v_mov_b32_e32 v93, v110
	v_mov_b32_e32 v91, v111
	v_pk_add_f32 v[100:101], v[100:101], v[104:105]
	v_pk_add_f32 v[90:91], v[92:93], v[90:91]
	s_nop 0
	v_pk_add_f32 v[90:91], v[90:91], v[100:101]
	s_nop 0
	v_add_f32_e32 v89, v90, v91
	s_nop 1
	v_add_f32_dpp v89, v89, v89 quad_perm:[1,0,3,2] row_mask:0xf bank_mask:0xf bound_ctrl:1
	s_nop 1
	v_add_f32_dpp v89, v89, v89 quad_perm:[2,3,0,1] row_mask:0xf bank_mask:0xf bound_ctrl:1
	s_nop 1
	v_add_f32_dpp v89, v89, v89 row_half_mirror row_mask:0xf bank_mask:0xf bound_ctrl:1
	s_nop 1
	v_add_f32_dpp v89, v89, v89 row_mirror row_mask:0xf bank_mask:0xf bound_ctrl:1
	s_nop 0
	v_readlane_b32 s0, v89, 16
	v_readlane_b32 s28, v89, 48
	v_readlane_b32 s26, v89, 0
	v_readlane_b32 s27, v89, 32
	v_mov_b32_e32 v90, s0
	v_mov_b32_e32 v91, s28
	v_pk_add_f32 v[90:91], s[26:27], v[90:91]
	s_nop 0
	v_add_f32_e32 v89, v90, v91
	v_fmamk_f32 v89, v89, 0x3a800000, v88
	v_rsq_f32_e32 v78, v89
	v_cvt_pk_bf16_f32 v34, v210, v211
	v_cvt_pk_bf16_f32 v35, v212, v213
	v_cvt_pk_bf16_f32 v36, v214, v215
	v_cvt_pk_bf16_f32 v37, v216, v217
	v_lshl_add_u64 v[70:71], v[64:65], 0, s[46:47]
	global_store_dwordx4 v[64:65], v[34:37], off
	s_nop 1
	v_cvt_pk_bf16_f32 v34, v218, v219
	v_cvt_pk_bf16_f32 v35, v220, v221
	v_cvt_pk_bf16_f32 v36, v222, v223
	v_cvt_pk_bf16_f32 v37, v224, v225
	s_nop 0
	global_store_dwordx4 v[70:71], v[34:37], off
	s_nop 1
	v_lshl_add_u64 v[64:65], v[64:65], 0, s[76:77]
	s_cmp_eq_u32 s97, 1
	s_cbranch_scc1 .Lp1_nw7
	s_waitcnt vmcnt(14)
.Lp1_nw7:
	v_pk_mul_f32 v[90:91], v[228:229], v[228:229]
	v_pk_mul_f32 v[92:93], v[226:227], v[226:227]
	v_pk_mul_f32 v[100:101], v[232:233], v[232:233]
	v_pk_mul_f32 v[102:103], v[230:231], v[230:231]
	v_pk_mov_b32 v[108:109], v[92:93], v[90:91] op_sel:[1,0]
	v_mov_b32_e32 v93, v91
	v_pk_mov_b32 v[90:91], v[102:103], v[100:101] op_sel:[1,0]
	v_mov_b32_e32 v103, v101
	v_mul_f32_e32 v107, v241, v241
	v_mul_f32_e32 v104, v235, v235
	v_mul_f32_e32 v106, v237, v237
	v_pk_add_f32 v[92:93], v[108:109], v[92:93]
	v_pk_add_f32 v[90:91], v[90:91], v[102:103]
	v_mul_f32_e32 v89, v240, v240
	v_mul_f32_e32 v110, v238, v238
	v_mul_f32_e32 v111, v239, v239
	v_pk_fma_f32 v[100:101], v[234:235], v[234:235], v[104:105] op_sel_hi:[1,1,0]
	v_pk_fma_f32 v[104:105], v[236:237], v[236:237], v[106:107] op_sel_hi:[1,1,0]
	v_pk_add_f32 v[92:93], v[92:93], v[92:93] op_sel:[0,1] op_sel_hi:[1,0]
	v_pk_add_f32 v[90:91], v[90:91], v[90:91] op_sel:[0,1] op_sel_hi:[1,0]
	v_mov_b32_e32 v101, v89
	v_mov_b32_e32 v105, v107
	v_mov_b32_e32 v93, v110
	v_mov_b32_e32 v91, v111
	v_pk_add_f32 v[100:101], v[100:101], v[104:105]
	v_pk_add_f32 v[90:91], v[92:93], v[90:91]
	s_nop 0
	v_pk_add_f32 v[90:91], v[90:91], v[100:101]
	s_nop 0
	v_add_f32_e32 v89, v90, v91
	s_nop 1
	v_add_f32_dpp v89, v89, v89 quad_perm:[1,0,3,2] row_mask:0xf bank_mask:0xf bound_ctrl:1
	s_nop 1
	v_add_f32_dpp v89, v89, v89 quad_perm:[2,3,0,1] row_mask:0xf bank_mask:0xf bound_ctrl:1
	s_nop 1
	v_add_f32_dpp v89, v89, v89 row_half_mirror row_mask:0xf bank_mask:0xf bound_ctrl:1
	s_nop 1
	v_add_f32_dpp v89, v89, v89 row_mirror row_mask:0xf bank_mask:0xf bound_ctrl:1
	s_nop 0
	v_readlane_b32 s0, v89, 16
	v_readlane_b32 s28, v89, 48
	v_readlane_b32 s26, v89, 0
	v_readlane_b32 s27, v89, 32
	v_mov_b32_e32 v90, s0
	v_mov_b32_e32 v91, s28
	v_pk_add_f32 v[90:91], s[26:27], v[90:91]
	s_nop 0
	v_add_f32_e32 v89, v90, v91
	v_fmamk_f32 v89, v89, 0x3a800000, v88
	v_rsq_f32_e32 v79, v89
	v_cvt_pk_bf16_f32 v34, v226, v227
	v_cvt_pk_bf16_f32 v35, v228, v229
	v_cvt_pk_bf16_f32 v36, v230, v231
	v_cvt_pk_bf16_f32 v37, v232, v233
	v_lshl_add_u64 v[70:71], v[64:65], 0, s[46:47]
	global_store_dwordx4 v[64:65], v[34:37], off
	s_nop 1
	v_cvt_pk_bf16_f32 v34, v234, v235
	v_cvt_pk_bf16_f32 v35, v236, v237
	v_cvt_pk_bf16_f32 v36, v238, v239
	v_cvt_pk_bf16_f32 v37, v240, v241
	s_nop 0
	global_store_dwordx4 v[70:71], v[34:37], off
	s_nop 1
	s_waitcnt vmcnt(16)
	v_mov_b64_e32 v[64:65], v[80:81]
	v_mov_b32_e32 v90, v72
	v_lshl_add_u64 v[66:67], v[64:65], 0, s[42:43]
	v_pk_mul_f32 v[92:93], v[114:115], v[90:91] op_sel_hi:[1,0]
	v_pk_mul_f32 v[100:101], v[116:117], v[90:91] op_sel_hi:[1,0]
	v_pk_mul_f32 v[102:103], v[118:119], v[90:91] op_sel_hi:[1,0]
	v_pk_mul_f32 v[104:105], v[120:121], v[90:91] op_sel_hi:[1,0]
	v_pk_mul_f32 v[106:107], v[122:123], v[90:91] op_sel_hi:[1,0]
	v_pk_mul_f32 v[108:109], v[124:125], v[90:91] op_sel_hi:[1,0]
	v_pk_mul_f32 v[110:111], v[126:127], v[90:91] op_sel_hi:[1,0]
	v_pk_mul_f32 v[90:91], v[128:129], v[90:91] op_sel_hi:[1,0]
	v_pk_fma_f32 v[92:93], v[10:11], v[92:93], v[6:7]
	v_pk_fma_f32 v[100:101], v[12:13], v[100:101], v[8:9]
	v_pk_fma_f32 v[102:103], v[18:19], v[102:103], v[2:3]
	v_pk_fma_f32 v[104:105], v[20:21], v[104:105], v[4:5]
	v_pk_fma_f32 v[108:109], v[24:25], v[108:109], v[32:33]
	v_pk_fma_f32 v[106:107], v[22:23], v[106:107], v[30:31]
	v_pk_fma_f32 v[112:113], v[16:17], v[90:91], v[28:29]
	v_pk_fma_f32 v[110:111], v[14:15], v[110:111], v[26:27]
	v_cvt_pk_bf16_f32 v90, v92, v93
	v_cvt_pk_bf16_f32 v91, v100, v101
	v_cvt_pk_bf16_f32 v92, v102, v103
	v_cvt_pk_bf16_f32 v93, v104, v105
	v_lshl_add_u64 v[68:69], v[64:65], 0, s[44:45]
	global_store_dwordx4 v[66:67], v[90:93], off
	s_nop 1
	v_cvt_pk_bf16_f32 v34, v106, v107
	v_cvt_pk_bf16_f32 v35, v108, v109
	v_cvt_pk_bf16_f32 v36, v110, v111
	v_cvt_pk_bf16_f32 v37, v112, v113
	s_nop 0
	global_store_dwordx4 v[68:69], v[34:37], off
	s_nop 1
	v_lshl_add_u64 v[64:65], v[64:65], 0, s[76:77]
	v_mov_b32_e32 v90, v73
	v_lshl_add_u64 v[66:67], v[64:65], 0, s[42:43]
	v_pk_mul_f32 v[92:93], v[130:131], v[90:91] op_sel_hi:[1,0]
	v_pk_mul_f32 v[100:101], v[132:133], v[90:91] op_sel_hi:[1,0]
	v_pk_mul_f32 v[102:103], v[134:135], v[90:91] op_sel_hi:[1,0]
	v_pk_mul_f32 v[104:105], v[136:137], v[90:91] op_sel_hi:[1,0]
	v_pk_mul_f32 v[106:107], v[138:139], v[90:91] op_sel_hi:[1,0]
	v_pk_mul_f32 v[108:109], v[140:141], v[90:91] op_sel_hi:[1,0]
	v_pk_mul_f32 v[110:111], v[142:143], v[90:91] op_sel_hi:[1,0]
	v_pk_mul_f32 v[90:91], v[144:145], v[90:91] op_sel_hi:[1,0]
	v_pk_fma_f32 v[92:93], v[10:11], v[92:93], v[6:7]
	v_pk_fma_f32 v[100:101], v[12:13], v[100:101], v[8:9]
	v_pk_fma_f32 v[102:103], v[18:19], v[102:103], v[2:3]
	v_pk_fma_f32 v[104:105], v[20:21], v[104:105], v[4:5]
	v_pk_fma_f32 v[108:109], v[24:25], v[108:109], v[32:33]
	v_pk_fma_f32 v[106:107], v[22:23], v[106:107], v[30:31]
	v_pk_fma_f32 v[112:113], v[16:17], v[90:91], v[28:29]
	v_pk_fma_f32 v[110:111], v[14:15], v[110:111], v[26:27]
	v_cvt_pk_bf16_f32 v90, v92, v93
	v_cvt_pk_bf16_f32 v91, v100, v101
	v_cvt_pk_bf16_f32 v92, v102, v103
	v_cvt_pk_bf16_f32 v93, v104, v105
	v_lshl_add_u64 v[68:69], v[64:65], 0, s[44:45]
	global_store_dwordx4 v[66:67], v[90:93], off
	s_nop 1
	v_cvt_pk_bf16_f32 v34, v106, v107
	v_cvt_pk_bf16_f32 v35, v108, v109
	v_cvt_pk_bf16_f32 v36, v110, v111
	v_cvt_pk_bf16_f32 v37, v112, v113
	s_nop 0
	global_store_dwordx4 v[68:69], v[34:37], off
	s_nop 1
	v_lshl_add_u64 v[64:65], v[64:65], 0, s[76:77]
	v_mov_b32_e32 v90, v74
	v_lshl_add_u64 v[66:67], v[64:65], 0, s[42:43]
	v_pk_mul_f32 v[92:93], v[146:147], v[90:91] op_sel_hi:[1,0]
	v_pk_mul_f32 v[100:101], v[148:149], v[90:91] op_sel_hi:[1,0]
	v_pk_mul_f32 v[102:103], v[150:151], v[90:91] op_sel_hi:[1,0]
	v_pk_mul_f32 v[104:105], v[152:153], v[90:91] op_sel_hi:[1,0]
	v_pk_mul_f32 v[106:107], v[154:155], v[90:91] op_sel_hi:[1,0]
	v_pk_mul_f32 v[108:109], v[156:157], v[90:91] op_sel_hi:[1,0]
	v_pk_mul_f32 v[110:111], v[158:159], v[90:91] op_sel_hi:[1,0]
	v_pk_mul_f32 v[90:91], v[160:161], v[90:91] op_sel_hi:[1,0]
	v_pk_fma_f32 v[92:93], v[10:11], v[92:93], v[6:7]
	v_pk_fma_f32 v[100:101], v[12:13], v[100:101], v[8:9]
	v_pk_fma_f32 v[102:103], v[18:19], v[102:103], v[2:3]
	v_pk_fma_f32 v[104:105], v[20:21], v[104:105], v[4:5]
	v_pk_fma_f32 v[108:109], v[24:25], v[108:109], v[32:33]
	v_pk_fma_f32 v[106:107], v[22:23], v[106:107], v[30:31]
	v_pk_fma_f32 v[112:113], v[16:17], v[90:91], v[28:29]
	v_pk_fma_f32 v[110:111], v[14:15], v[110:111], v[26:27]
	v_cvt_pk_bf16_f32 v90, v92, v93
	v_cvt_pk_bf16_f32 v91, v100, v101
	v_cvt_pk_bf16_f32 v92, v102, v103
	v_cvt_pk_bf16_f32 v93, v104, v105
	v_lshl_add_u64 v[68:69], v[64:65], 0, s[44:45]
	global_store_dwordx4 v[66:67], v[90:93], off
	s_nop 1
	v_cvt_pk_bf16_f32 v34, v106, v107
	v_cvt_pk_bf16_f32 v35, v108, v109
	v_cvt_pk_bf16_f32 v36, v110, v111
	v_cvt_pk_bf16_f32 v37, v112, v113
	s_nop 0
	global_store_dwordx4 v[68:69], v[34:37], off
	s_nop 1
	v_lshl_add_u64 v[64:65], v[64:65], 0, s[76:77]
	v_mov_b32_e32 v90, v75
	v_lshl_add_u64 v[66:67], v[64:65], 0, s[42:43]
	v_pk_mul_f32 v[92:93], v[162:163], v[90:91] op_sel_hi:[1,0]
	v_pk_mul_f32 v[100:101], v[164:165], v[90:91] op_sel_hi:[1,0]
	v_pk_mul_f32 v[102:103], v[166:167], v[90:91] op_sel_hi:[1,0]
	v_pk_mul_f32 v[104:105], v[168:169], v[90:91] op_sel_hi:[1,0]
	v_pk_mul_f32 v[106:107], v[170:171], v[90:91] op_sel_hi:[1,0]
	v_pk_mul_f32 v[108:109], v[172:173], v[90:91] op_sel_hi:[1,0]
	v_pk_mul_f32 v[110:111], v[174:175], v[90:91] op_sel_hi:[1,0]
	v_pk_mul_f32 v[90:91], v[176:177], v[90:91] op_sel_hi:[1,0]
	v_pk_fma_f32 v[92:93], v[10:11], v[92:93], v[6:7]
	v_pk_fma_f32 v[100:101], v[12:13], v[100:101], v[8:9]
	v_pk_fma_f32 v[102:103], v[18:19], v[102:103], v[2:3]
	v_pk_fma_f32 v[104:105], v[20:21], v[104:105], v[4:5]
	v_pk_fma_f32 v[108:109], v[24:25], v[108:109], v[32:33]
	v_pk_fma_f32 v[106:107], v[22:23], v[106:107], v[30:31]
	v_pk_fma_f32 v[112:113], v[16:17], v[90:91], v[28:29]
	v_pk_fma_f32 v[110:111], v[14:15], v[110:111], v[26:27]
	v_cvt_pk_bf16_f32 v90, v92, v93
	v_cvt_pk_bf16_f32 v91, v100, v101
	v_cvt_pk_bf16_f32 v92, v102, v103
	v_cvt_pk_bf16_f32 v93, v104, v105
	v_lshl_add_u64 v[68:69], v[64:65], 0, s[44:45]
	global_store_dwordx4 v[66:67], v[90:93], off
	s_nop 1
	v_cvt_pk_bf16_f32 v34, v106, v107
	v_cvt_pk_bf16_f32 v35, v108, v109
	v_cvt_pk_bf16_f32 v36, v110, v111
	v_cvt_pk_bf16_f32 v37, v112, v113
	s_nop 0
	global_store_dwordx4 v[68:69], v[34:37], off
	s_nop 1
	v_lshl_add_u64 v[64:65], v[64:65], 0, s[76:77]
	v_mov_b32_e32 v90, v76
	v_lshl_add_u64 v[66:67], v[64:65], 0, s[42:43]
	v_pk_mul_f32 v[92:93], v[178:179], v[90:91] op_sel_hi:[1,0]
	v_pk_mul_f32 v[100:101], v[180:181], v[90:91] op_sel_hi:[1,0]
	v_pk_mul_f32 v[102:103], v[182:183], v[90:91] op_sel_hi:[1,0]
	v_pk_mul_f32 v[104:105], v[184:185], v[90:91] op_sel_hi:[1,0]
	v_pk_mul_f32 v[106:107], v[186:187], v[90:91] op_sel_hi:[1,0]
	v_pk_mul_f32 v[108:109], v[188:189], v[90:91] op_sel_hi:[1,0]
	v_pk_mul_f32 v[110:111], v[190:191], v[90:91] op_sel_hi:[1,0]
	v_pk_mul_f32 v[90:91], v[192:193], v[90:91] op_sel_hi:[1,0]
	v_pk_fma_f32 v[92:93], v[10:11], v[92:93], v[6:7]
	v_pk_fma_f32 v[100:101], v[12:13], v[100:101], v[8:9]
	v_pk_fma_f32 v[102:103], v[18:19], v[102:103], v[2:3]
	v_pk_fma_f32 v[104:105], v[20:21], v[104:105], v[4:5]
	v_pk_fma_f32 v[108:109], v[24:25], v[108:109], v[32:33]
	v_pk_fma_f32 v[106:107], v[22:23], v[106:107], v[30:31]
	v_pk_fma_f32 v[112:113], v[16:17], v[90:91], v[28:29]
	v_pk_fma_f32 v[110:111], v[14:15], v[110:111], v[26:27]
	v_cvt_pk_bf16_f32 v90, v92, v93
	v_cvt_pk_bf16_f32 v91, v100, v101
	v_cvt_pk_bf16_f32 v92, v102, v103
	v_cvt_pk_bf16_f32 v93, v104, v105
	v_lshl_add_u64 v[68:69], v[64:65], 0, s[44:45]
	global_store_dwordx4 v[66:67], v[90:93], off
	s_nop 1
	v_cvt_pk_bf16_f32 v34, v106, v107
	v_cvt_pk_bf16_f32 v35, v108, v109
	v_cvt_pk_bf16_f32 v36, v110, v111
	v_cvt_pk_bf16_f32 v37, v112, v113
	s_nop 0
	global_store_dwordx4 v[68:69], v[34:37], off
	s_nop 1
	v_lshl_add_u64 v[64:65], v[64:65], 0, s[76:77]
	v_mov_b32_e32 v90, v77
	v_lshl_add_u64 v[66:67], v[64:65], 0, s[42:43]
	v_pk_mul_f32 v[92:93], v[194:195], v[90:91] op_sel_hi:[1,0]
	v_pk_mul_f32 v[100:101], v[196:197], v[90:91] op_sel_hi:[1,0]
	v_pk_mul_f32 v[102:103], v[198:199], v[90:91] op_sel_hi:[1,0]
	v_pk_mul_f32 v[104:105], v[200:201], v[90:91] op_sel_hi:[1,0]
	v_pk_mul_f32 v[106:107], v[202:203], v[90:91] op_sel_hi:[1,0]
	v_pk_mul_f32 v[108:109], v[204:205], v[90:91] op_sel_hi:[1,0]
	v_pk_mul_f32 v[110:111], v[206:207], v[90:91] op_sel_hi:[1,0]
	v_pk_mul_f32 v[90:91], v[208:209], v[90:91] op_sel_hi:[1,0]
	v_pk_fma_f32 v[92:93], v[10:11], v[92:93], v[6:7]
	v_pk_fma_f32 v[100:101], v[12:13], v[100:101], v[8:9]
	v_pk_fma_f32 v[102:103], v[18:19], v[102:103], v[2:3]
	v_pk_fma_f32 v[104:105], v[20:21], v[104:105], v[4:5]
	v_pk_fma_f32 v[108:109], v[24:25], v[108:109], v[32:33]
	v_pk_fma_f32 v[106:107], v[22:23], v[106:107], v[30:31]
	v_pk_fma_f32 v[112:113], v[16:17], v[90:91], v[28:29]
	v_pk_fma_f32 v[110:111], v[14:15], v[110:111], v[26:27]
	v_cvt_pk_bf16_f32 v90, v92, v93
	v_cvt_pk_bf16_f32 v91, v100, v101
	v_cvt_pk_bf16_f32 v92, v102, v103
	v_cvt_pk_bf16_f32 v93, v104, v105
	v_lshl_add_u64 v[68:69], v[64:65], 0, s[44:45]
	global_store_dwordx4 v[66:67], v[90:93], off
	s_nop 1
	v_cvt_pk_bf16_f32 v34, v106, v107
	v_cvt_pk_bf16_f32 v35, v108, v109
	v_cvt_pk_bf16_f32 v36, v110, v111
	v_cvt_pk_bf16_f32 v37, v112, v113
	s_nop 0
	global_store_dwordx4 v[68:69], v[34:37], off
	s_nop 1
	v_lshl_add_u64 v[64:65], v[64:65], 0, s[76:77]
	v_mov_b32_e32 v90, v78
	v_lshl_add_u64 v[66:67], v[64:65], 0, s[42:43]
	v_pk_mul_f32 v[92:93], v[210:211], v[90:91] op_sel_hi:[1,0]
	v_pk_mul_f32 v[100:101], v[212:213], v[90:91] op_sel_hi:[1,0]
	v_pk_mul_f32 v[102:103], v[214:215], v[90:91] op_sel_hi:[1,0]
	v_pk_mul_f32 v[104:105], v[216:217], v[90:91] op_sel_hi:[1,0]
	v_pk_mul_f32 v[106:107], v[218:219], v[90:91] op_sel_hi:[1,0]
	v_pk_mul_f32 v[108:109], v[220:221], v[90:91] op_sel_hi:[1,0]
	v_pk_mul_f32 v[110:111], v[222:223], v[90:91] op_sel_hi:[1,0]
	v_pk_mul_f32 v[90:91], v[224:225], v[90:91] op_sel_hi:[1,0]
	v_pk_fma_f32 v[92:93], v[10:11], v[92:93], v[6:7]
	v_pk_fma_f32 v[100:101], v[12:13], v[100:101], v[8:9]
	v_pk_fma_f32 v[102:103], v[18:19], v[102:103], v[2:3]
	v_pk_fma_f32 v[104:105], v[20:21], v[104:105], v[4:5]
	v_pk_fma_f32 v[108:109], v[24:25], v[108:109], v[32:33]
	v_pk_fma_f32 v[106:107], v[22:23], v[106:107], v[30:31]
	v_pk_fma_f32 v[112:113], v[16:17], v[90:91], v[28:29]
	v_pk_fma_f32 v[110:111], v[14:15], v[110:111], v[26:27]
	v_cvt_pk_bf16_f32 v90, v92, v93
	v_cvt_pk_bf16_f32 v91, v100, v101
	v_cvt_pk_bf16_f32 v92, v102, v103
	v_cvt_pk_bf16_f32 v93, v104, v105
	v_lshl_add_u64 v[68:69], v[64:65], 0, s[44:45]
	global_store_dwordx4 v[66:67], v[90:93], off
	s_nop 1
	v_cvt_pk_bf16_f32 v34, v106, v107
	v_cvt_pk_bf16_f32 v35, v108, v109
	v_cvt_pk_bf16_f32 v36, v110, v111
	v_cvt_pk_bf16_f32 v37, v112, v113
	s_nop 0
	global_store_dwordx4 v[68:69], v[34:37], off
	s_nop 1
	v_lshl_add_u64 v[64:65], v[64:65], 0, s[76:77]
	v_mov_b32_e32 v90, v79
	v_lshl_add_u64 v[66:67], v[64:65], 0, s[42:43]
	v_pk_mul_f32 v[92:93], v[226:227], v[90:91] op_sel_hi:[1,0]
	v_pk_mul_f32 v[100:101], v[228:229], v[90:91] op_sel_hi:[1,0]
	v_pk_mul_f32 v[102:103], v[230:231], v[90:91] op_sel_hi:[1,0]
	v_pk_mul_f32 v[104:105], v[232:233], v[90:91] op_sel_hi:[1,0]
	v_pk_mul_f32 v[106:107], v[234:235], v[90:91] op_sel_hi:[1,0]
	v_pk_mul_f32 v[108:109], v[236:237], v[90:91] op_sel_hi:[1,0]
	v_pk_mul_f32 v[110:111], v[238:239], v[90:91] op_sel_hi:[1,0]
	v_pk_mul_f32 v[90:91], v[240:241], v[90:91] op_sel_hi:[1,0]
	v_pk_fma_f32 v[92:93], v[10:11], v[92:93], v[6:7]
	v_pk_fma_f32 v[100:101], v[12:13], v[100:101], v[8:9]
	v_pk_fma_f32 v[102:103], v[18:19], v[102:103], v[2:3]
	v_pk_fma_f32 v[104:105], v[20:21], v[104:105], v[4:5]
	v_pk_fma_f32 v[108:109], v[24:25], v[108:109], v[32:33]
	v_pk_fma_f32 v[106:107], v[22:23], v[106:107], v[30:31]
	v_pk_fma_f32 v[112:113], v[16:17], v[90:91], v[28:29]
	v_pk_fma_f32 v[110:111], v[14:15], v[110:111], v[26:27]
	v_cvt_pk_bf16_f32 v90, v92, v93
	v_cvt_pk_bf16_f32 v91, v100, v101
	v_cvt_pk_bf16_f32 v92, v102, v103
	v_cvt_pk_bf16_f32 v93, v104, v105
	v_lshl_add_u64 v[68:69], v[64:65], 0, s[44:45]
	global_store_dwordx4 v[66:67], v[90:93], off
	s_nop 1
	v_cvt_pk_bf16_f32 v34, v106, v107
	v_cvt_pk_bf16_f32 v35, v108, v109
	v_cvt_pk_bf16_f32 v36, v110, v111
	v_cvt_pk_bf16_f32 v37, v112, v113
	s_nop 0
	global_store_dwordx4 v[68:69], v[34:37], off
	s_nop 1
	s_add_i32 s4, s4, s6
	v_lshl_add_u64 v[58:59], v[58:59], 0, s[22:23]
	s_cmpk_gt_i32 s4, 0x3fff
	v_lshl_add_u64 v[60:61], v[60:61], 0, s[36:37]
	s_cbranch_scc0 .LBB0_157

.LBB0_215:
	s_and_b64 vcc, exec, s[4:5]
	s_cbranch_vccz .LBB0_232
	s_waitcnt vmcnt(0)
	s_barrier
	s_and_saveexec_b64 s[4:5], s[58:59]
	s_cbranch_execz .LBB0_231
	s_cmp_eq_u32 s100, 0
	s_cbranch_scc1 .Lwb_skip_tb1
	buffer_wbl2 sc1
	s_waitcnt vmcnt(0)
.Lwb_skip_tb1:
	v_readlane_b32 s0, v250, 13
	s_lshl_b32 s6, s0, 6
	s_ashr_i32 s7, s6, 31
	s_lshl_b64 s[6:7], s[6:7], 2
	s_mov_b64 s[22:23], exec
	s_add_u32 s0, s34, s6
	s_addc_u32 s7, s35, s7
	v_mbcnt_lo_u32_b32 v2, s22, 0
	s_add_u32 s6, s0, 0x40000
	v_mbcnt_hi_u32_b32 v2, s23, v2
	s_addc_u32 s7, s7, 0
	v_cmp_eq_u32_e32 vcc, 0, v2
	s_and_saveexec_b64 s[36:37], vcc
	s_cbranch_execz .LBB0_219
	s_bcnt1_i32_b64 s0, s[22:23]
	v_mov_b32_e32 v2, 0
	v_mov_b32_e32 v3, s0
	global_atomic_add v2, v3, s[6:7]

.LBB0_362:
	s_and_b64 vcc, exec, s[4:5]
	s_cbranch_vccz .LBB0_383
	s_waitcnt vmcnt(0)
	s_waitcnt lgkmcnt(0)
	s_barrier
	s_and_saveexec_b64 s[4:5], s[58:59]
	s_cbranch_execz .LBB0_382
	s_cmp_eq_u32 s100, 0
	s_cbranch_scc1 .Lwb_skip_tb2
	buffer_wbl2 sc1
	s_waitcnt vmcnt(0)
.Lwb_skip_tb2:
	v_readlane_b32 s0, v250, 13
	s_lshl_b32 s6, s0, 6
	s_ashr_i32 s7, s6, 31
	s_lshl_b64 s[6:7], s[6:7], 2
	s_mov_b64 s[10:11], exec
	s_add_u32 s0, s34, s6
	s_addc_u32 s7, s35, s7
	v_mbcnt_lo_u32_b32 v2, s10, 0
	s_add_u32 s6, s0, 0x40000
	v_mbcnt_hi_u32_b32 v2, s11, v2
	s_addc_u32 s7, s7, 0
	v_cmp_eq_u32_e32 vcc, 0, v2
	s_and_saveexec_b64 s[20:21], vcc
	s_cbranch_execz .LBB0_366
	s_bcnt1_i32_b64 s0, s[10:11]
	v_mov_b32_e32 v2, 0
	v_mov_b32_e32 v3, s0
	global_atomic_add v2, v3, s[6:7]

.LBB0_427:
	s_waitcnt lgkmcnt(1)
	v_lshlrev_b32_e32 v236, 16, v138
	v_and_b32_e32 v237, 0xffff0000, v138
	v_lshlrev_b32_e32 v238, 16, v139
	v_and_b32_e32 v239, 0xffff0000, v139
	v_lshlrev_b32_e32 v240, 16, v140
	v_and_b32_e32 v241, 0xffff0000, v140
	v_lshlrev_b32_e32 v242, 16, v141
	v_and_b32_e32 v243, 0xffff0000, v141
	v_pk_fma_f32 v[202:203], v[98:99], v[236:237], v[200:201]
	v_pk_fma_f32 v[200:201], v[100:101], v[238:239], v[204:205]
	v_pk_fma_f32 v[138:139], v[96:97], v[242:243], v[208:209]
	v_pk_fma_f32 v[90:91], v[90:91], v[236:237], v[210:211]
	v_pk_fma_f32 v[86:87], v[86:87], v[240:241], v[214:215]
	s_waitcnt lgkmcnt(0)
	v_lshlrev_b32_e32 v204, 16, v134
	v_and_b32_e32 v205, 0xffff0000, v134
	v_lshlrev_b32_e32 v208, 16, v136
	v_and_b32_e32 v209, 0xffff0000, v136
	v_pk_fma_f32 v[140:141], v[94:95], v[240:241], v[206:207]
	v_pk_fma_f32 v[88:89], v[88:89], v[242:243], v[216:217]
	v_lshlrev_b32_e32 v206, 16, v135
	v_and_b32_e32 v207, 0xffff0000, v135
	v_lshlrev_b32_e32 v136, 16, v137
	v_and_b32_e32 v137, 0xffff0000, v137
	v_pk_fma_f32 v[134:135], v[98:99], v[204:205], v[90:91]
	v_pk_fma_f32 v[98:99], v[94:95], v[208:209], v[86:87]
	v_lshlrev_b32_e32 v86, 16, v42
	v_and_b32_e32 v87, 0xffff0000, v42
	v_pk_fma_f32 v[92:93], v[92:93], v[238:239], v[212:213]
	v_pk_fma_f32 v[94:95], v[96:97], v[136:137], v[88:89]
	v_lshlrev_b32_e32 v96, 16, v38
	v_and_b32_e32 v97, 0xffff0000, v38
	v_lshlrev_b32_e32 v212, 16, v30
	v_and_b32_e32 v213, 0xffff0000, v30
	v_lshlrev_b32_e32 v214, 16, v31
	v_and_b32_e32 v215, 0xffff0000, v31
	s_waitcnt vmcnt(0)
	v_pk_fma_f32 v[30:31], v[122:123], v[86:87], v[130:131]
	v_lshlrev_b32_e32 v208, 16, v34
	v_and_b32_e32 v209, 0xffff0000, v34
	v_pk_fma_f32 v[30:31], v[126:127], v[96:97], v[30:31]
	v_lshlrev_b32_e32 v88, 16, v43
	v_and_b32_e32 v89, 0xffff0000, v43
	v_lshlrev_b32_e32 v242, 16, v22
	v_and_b32_e32 v243, 0xffff0000, v22
	v_lshlrev_b32_e32 v244, 16, v23
	v_and_b32_e32 v245, 0xffff0000, v23
	v_lshlrev_b32_e32 v22, 16, v18
	v_and_b32_e32 v23, 0xffff0000, v18
	v_pk_fma_f32 v[30:31], v[118:119], v[208:209], v[30:31]
	v_lshlrev_b32_e32 v136, 16, v39
	v_and_b32_e32 v137, 0xffff0000, v39
	v_pk_mul_f32 v[42:43], v[30:31], v[22:23]
	v_pk_fma_f32 v[22:23], v[124:125], v[88:89], v[132:133]
	v_lshlrev_b32_e32 v34, 16, v35
	v_and_b32_e32 v35, 0xffff0000, v35
	v_pk_fma_f32 v[22:23], v[128:129], v[136:137], v[22:23]
	v_lshlrev_b32_e32 v90, 16, v44
	v_and_b32_e32 v91, 0xffff0000, v44
	v_lshlrev_b32_e32 v18, 16, v19
	v_and_b32_e32 v19, 0xffff0000, v19
	v_pk_fma_f32 v[22:23], v[120:121], v[34:35], v[22:23]
	v_lshlrev_b32_e32 v204, 16, v40
	v_and_b32_e32 v205, 0xffff0000, v40
	v_pk_mul_f32 v[88:89], v[22:23], v[18:19]
	v_pk_fma_f32 v[18:19], v[102:103], v[90:91], v[114:115]
	v_lshlrev_b32_e32 v210, 16, v36
	v_and_b32_e32 v211, 0xffff0000, v36
	v_pk_fma_f32 v[18:19], v[110:111], v[204:205], v[18:19]
	v_lshlrev_b32_e32 v44, 16, v45
	v_and_b32_e32 v45, 0xffff0000, v45
	v_lshlrev_b32_e32 v246, 16, v24
	v_and_b32_e32 v247, 0xffff0000, v24
	v_lshlrev_b32_e32 v248, 16, v25
	v_and_b32_e32 v249, 0xffff0000, v25
	v_lshlrev_b32_e32 v24, 16, v20
	v_and_b32_e32 v25, 0xffff0000, v20
	v_pk_fma_f32 v[18:19], v[106:107], v[210:211], v[18:19]
	v_pk_fma_f32 v[100:101], v[100:101], v[206:207], v[92:93]
	v_lshlrev_b32_e32 v206, 16, v41
	v_and_b32_e32 v207, 0xffff0000, v41
	v_pk_mul_f32 v[90:91], v[18:19], v[24:25]
	v_pk_fma_f32 v[18:19], v[104:105], v[44:45], v[116:117]
	v_lshlrev_b32_e32 v36, 16, v37
	v_and_b32_e32 v37, 0xffff0000, v37
	v_pk_fma_f32 v[18:19], v[112:113], v[206:207], v[18:19]
	v_pk_fma_f32 v[22:23], v[122:123], v[96:97], v[130:131]
	v_lshlrev_b32_e32 v20, 16, v21
	v_and_b32_e32 v21, 0xffff0000, v21
	v_pk_fma_f32 v[18:19], v[108:109], v[36:37], v[18:19]
	v_pk_fma_f32 v[22:23], v[126:127], v[208:209], v[22:23]
	v_pk_mul_f32 v[92:93], v[18:19], v[20:21]
	v_lshlrev_b32_e32 v18, 16, v14
	v_and_b32_e32 v19, 0xffff0000, v14
	v_pk_fma_f32 v[22:23], v[118:119], v[212:213], v[22:23]
	v_lshlrev_b32_e32 v14, 16, v15
	v_pk_mul_f32 v[38:39], v[22:23], v[18:19]
	v_pk_fma_f32 v[18:19], v[124:125], v[136:137], v[132:133]
	v_and_b32_e32 v15, 0xffff0000, v15
	v_pk_fma_f32 v[18:19], v[128:129], v[34:35], v[18:19]
	v_lshlrev_b32_e32 v216, 16, v32
	v_pk_fma_f32 v[18:19], v[120:121], v[214:215], v[18:19]
	v_and_b32_e32 v217, 0xffff0000, v32
	v_pk_mul_f32 v[40:41], v[18:19], v[14:15]
	v_pk_fma_f32 v[14:15], v[102:103], v[204:205], v[114:115]
	v_lshlrev_b32_e32 v20, 16, v16
	v_pk_fma_f32 v[14:15], v[110:111], v[210:211], v[14:15]
	v_and_b32_e32 v21, 0xffff0000, v16
	v_pk_fma_f32 v[14:15], v[106:107], v[216:217], v[14:15]
	v_lshlrev_b32_e32 v236, 16, v33
	v_pk_mul_f32 v[44:45], v[14:15], v[20:21]
	v_pk_fma_f32 v[14:15], v[104:105], v[206:207], v[116:117]
	v_and_b32_e32 v237, 0xffff0000, v33
	v_pk_fma_f32 v[14:15], v[112:113], v[36:37], v[14:15]
	v_pk_fma_f32 v[18:19], v[122:123], v[208:209], v[130:131]
	v_lshlrev_b32_e32 v238, 16, v26
	v_and_b32_e32 v239, 0xffff0000, v26
	v_lshlrev_b32_e32 v16, 16, v17
	v_and_b32_e32 v17, 0xffff0000, v17
	v_pk_fma_f32 v[14:15], v[108:109], v[236:237], v[14:15]
	v_pk_fma_f32 v[18:19], v[126:127], v[212:213], v[18:19]
	v_pk_mul_f32 v[86:87], v[14:15], v[16:17]
	v_lshlrev_b32_e32 v14, 16, v10
	v_and_b32_e32 v15, 0xffff0000, v10
	v_pk_fma_f32 v[18:19], v[118:119], v[238:239], v[18:19]
	v_lshlrev_b32_e32 v26, 16, v27
	v_pk_mul_f32 v[30:31], v[18:19], v[14:15]
	v_pk_fma_f32 v[14:15], v[124:125], v[34:35], v[132:133]
	v_and_b32_e32 v27, 0xffff0000, v27
	v_pk_fma_f32 v[14:15], v[128:129], v[214:215], v[14:15]
	v_lshlrev_b32_e32 v10, 16, v11
	v_and_b32_e32 v11, 0xffff0000, v11
	v_pk_fma_f32 v[14:15], v[120:121], v[26:27], v[14:15]
	v_lshlrev_b32_e32 v240, 16, v28
	v_pk_mul_f32 v[32:33], v[14:15], v[10:11]
	v_pk_fma_f32 v[10:11], v[102:103], v[210:211], v[114:115]
	v_and_b32_e32 v241, 0xffff0000, v28
	v_pk_fma_f32 v[10:11], v[110:111], v[216:217], v[10:11]
	v_lshlrev_b32_e32 v16, 16, v12
	v_and_b32_e32 v17, 0xffff0000, v12
	v_pk_fma_f32 v[10:11], v[106:107], v[240:241], v[10:11]
	v_lshlrev_b32_e32 v28, 16, v29
	v_pk_mul_f32 v[34:35], v[10:11], v[16:17]
	v_pk_fma_f32 v[10:11], v[104:105], v[36:37], v[116:117]
	v_and_b32_e32 v29, 0xffff0000, v29
	v_pk_fma_f32 v[10:11], v[112:113], v[236:237], v[10:11]
	v_pk_fma_f32 v[14:15], v[122:123], v[212:213], v[130:131]
	v_lshlrev_b32_e32 v12, 16, v13
	v_and_b32_e32 v13, 0xffff0000, v13
	v_pk_fma_f32 v[10:11], v[108:109], v[28:29], v[10:11]
	v_pk_fma_f32 v[14:15], v[126:127], v[238:239], v[14:15]
	v_pk_mul_f32 v[36:37], v[10:11], v[12:13]
	v_lshlrev_b32_e32 v10, 16, v6
	v_and_b32_e32 v11, 0xffff0000, v6
	v_pk_fma_f32 v[14:15], v[118:119], v[242:243], v[14:15]
	v_lshlrev_b32_e32 v6, 16, v7
	v_pk_mul_f32 v[22:23], v[14:15], v[10:11]
	v_pk_fma_f32 v[10:11], v[124:125], v[214:215], v[132:133]
	v_and_b32_e32 v7, 0xffff0000, v7
	v_pk_fma_f32 v[10:11], v[128:129], v[26:27], v[10:11]
	v_lshlrev_b32_e32 v12, 16, v8
	v_pk_fma_f32 v[10:11], v[120:121], v[244:245], v[10:11]
	v_and_b32_e32 v13, 0xffff0000, v8
	v_pk_mul_f32 v[24:25], v[10:11], v[6:7]
	v_pk_fma_f32 v[6:7], v[102:103], v[216:217], v[114:115]
	v_lshlrev_b32_e32 v8, 16, v9
	v_pk_fma_f32 v[6:7], v[110:111], v[240:241], v[6:7]
	v_and_b32_e32 v9, 0xffff0000, v9
	v_pk_fma_f32 v[6:7], v[106:107], v[246:247], v[6:7]
	v_pk_mul_f32 v[10:11], v[192:193], v[192:193]
	v_pk_mul_f32 v[26:27], v[6:7], v[12:13]
	v_pk_fma_f32 v[6:7], v[104:105], v[236:237], v[116:117]
	v_pk_fma_f32 v[10:11], v[194:195], v[194:195], v[10:11]
	v_pk_fma_f32 v[6:7], v[112:113], v[28:29], v[6:7]
	s_add_i32 s48, s17, s95
	v_pk_fma_f32 v[6:7], v[108:109], v[248:249], v[6:7]
	s_ashr_i32 s49, s48, 31
	v_pk_mul_f32 v[28:29], v[6:7], v[8:9]
	v_pk_add_f32 v[6:7], v[198:199], v[196:197]
	v_pk_add_f32 v[8:9], v[194:195], v[192:193]
	s_lshl_b64 s[48:49], s[48:49], 11
	v_pk_add_f32 v[6:7], v[6:7], v[8:9]
	v_pk_mul_f32 v[8:9], v[196:197], v[196:197]
	v_add_f32_e32 v12, v6, v7
	v_pk_fma_f32 v[8:9], v[198:199], v[198:199], v[8:9]
	v_pk_add_f32 v[6:7], v[190:191], v[188:189]
	v_pk_add_f32 v[8:9], v[8:9], v[10:11]
	v_pk_mul_f32 v[10:11], v[184:185], v[184:185]
	v_add_f32_e32 v13, v8, v9
	v_pk_add_f32 v[8:9], v[186:187], v[184:185]
	v_pk_fma_f32 v[10:11], v[186:187], v[186:187], v[10:11]
	v_pk_add_f32 v[6:7], v[6:7], v[8:9]
	v_pk_mul_f32 v[8:9], v[188:189], v[188:189]
	v_add_f32_e32 v103, v6, v7
	v_pk_fma_f32 v[8:9], v[190:191], v[190:191], v[8:9]
	v_pk_add_f32 v[6:7], v[202:203], v[200:201]
	v_pk_add_f32 v[8:9], v[8:9], v[10:11]
	v_pk_mul_f32 v[10:11], v[138:139], v[138:139]
	v_add_f32_e32 v105, v8, v9
	v_pk_add_f32 v[8:9], v[140:141], v[138:139]
	v_pk_fma_f32 v[10:11], v[140:141], v[140:141], v[10:11]
	v_pk_add_f32 v[6:7], v[6:7], v[8:9]
	v_pk_mul_f32 v[8:9], v[200:201], v[200:201]
	v_add_f32_e32 v109, v6, v7
	v_pk_fma_f32 v[8:9], v[202:203], v[202:203], v[8:9]
	v_pk_add_f32 v[6:7], v[134:135], v[100:101]
	v_pk_add_f32 v[8:9], v[8:9], v[10:11]
	v_lshl_add_u64 v[182:183], v[160:161], 0, s[48:49]
	v_add_f32_e32 v111, v8, v9
	v_pk_add_f32 v[8:9], v[98:99], v[94:95]
	v_pk_mul_f32 v[10:11], v[94:95], v[94:95]
	v_pk_add_f32 v[6:7], v[6:7], v[8:9]
	v_pk_mul_f32 v[8:9], v[100:101], v[100:101]
	v_add_f32_e32 v117, v6, v7
	v_add_f32_dpp v6, v12, v12 quad_perm:[1,0,3,2] row_mask:0xf bank_mask:0xf bound_ctrl:1
	v_pk_fma_f32 v[8:9], v[134:135], v[134:135], v[8:9]
	v_pk_fma_f32 v[10:11], v[98:99], v[98:99], v[10:11]
	v_add_f32_dpp v6, v6, v6 quad_perm:[2,3,0,1] row_mask:0xf bank_mask:0xf bound_ctrl:1
	v_pk_add_f32 v[8:9], v[8:9], v[10:11]
	v_add_f32_dpp v103, v103, v103 quad_perm:[1,0,3,2] row_mask:0xf bank_mask:0xf bound_ctrl:1
	v_add_f32_dpp v6, v6, v6 row_half_mirror row_mask:0xf bank_mask:0xf bound_ctrl:1
	v_add_f32_e32 v119, v8, v9
	v_add_f32_dpp v103, v103, v103 quad_perm:[2,3,0,1] row_mask:0xf bank_mask:0xf bound_ctrl:1
	v_add_f32_dpp v6, v6, v6 row_mirror row_mask:0xf bank_mask:0xf bound_ctrl:1
	s_mov_b32 s95, 32
	v_readlane_b32 s0, v6, 16
	v_readlane_b32 s50, v6, 48
	v_readlane_b32 s48, v6, 0
	v_readlane_b32 s49, v6, 32
	v_mov_b32_e32 v6, s0
	v_mov_b32_e32 v7, s50
	v_pk_add_f32 v[96:97], s[48:49], v[6:7]
	v_add_f32_dpp v6, v13, v13 quad_perm:[1,0,3,2] row_mask:0xf bank_mask:0xf bound_ctrl:1
	v_add_f32_dpp v103, v103, v103 row_half_mirror row_mask:0xf bank_mask:0xf bound_ctrl:1
	s_and_b64 vcc, exec, s[46:47]
	v_add_f32_dpp v6, v6, v6 quad_perm:[2,3,0,1] row_mask:0xf bank_mask:0xf bound_ctrl:1
	v_add_f32_dpp v103, v103, v103 row_mirror row_mask:0xf bank_mask:0xf bound_ctrl:1
	s_nop 0
	v_add_f32_dpp v6, v6, v6 row_half_mirror row_mask:0xf bank_mask:0xf bound_ctrl:1
	s_nop 1
	v_add_f32_dpp v6, v6, v6 row_mirror row_mask:0xf bank_mask:0xf bound_ctrl:1
	s_nop 0
	v_readlane_b32 s48, v6, 16
	v_readlane_b32 s0, v6, 0
	v_readlane_b32 s49, v6, 32
	v_readlane_b32 s50, v6, 48
	v_mov_b32_e32 v6, s48
	v_add_f32_e32 v102, s0, v6
	global_load_dwordx4 v[6:9], v[154:155], off offset:16
	global_load_dwordx4 v[14:17], v[154:155], off
	global_load_dwordx4 v[10:13], v[156:157], off offset:16
	global_load_dwordx4 v[18:21], v[156:157], off
	v_mov_b32_e32 v104, s50
	v_add_f32_e32 v104, s49, v104
	v_readlane_b32 s48, v103, 0
	v_readlane_b32 s0, v103, 16
	v_readlane_b32 s49, v103, 32
	v_readlane_b32 s50, v103, 48
	v_add_f32_dpp v103, v105, v105 quad_perm:[1,0,3,2] row_mask:0xf bank_mask:0xf bound_ctrl:1
	v_mov_b32_e32 v106, s0
	v_mov_b32_e32 v107, s50
	v_add_f32_dpp v103, v103, v103 quad_perm:[2,3,0,1] row_mask:0xf bank_mask:0xf bound_ctrl:1
	v_pk_add_f32 v[106:107], s[48:49], v[106:107]
	v_mov_b32_e32 v105, v97
	v_add_f32_dpp v103, v103, v103 row_half_mirror row_mask:0xf bank_mask:0xf bound_ctrl:1
	s_nop 1
	v_add_f32_dpp v103, v103, v103 row_mirror row_mask:0xf bank_mask:0xf bound_ctrl:1
	s_nop 0
	v_readlane_b32 s48, v103, 16
	v_readlane_b32 s0, v103, 0
	v_readlane_b32 s49, v103, 32
	v_readlane_b32 s50, v103, 48
	v_mov_b32_e32 v103, s48
	v_add_f32_e32 v108, s0, v103
	v_mov_b32_e32 v103, s50
	v_add_f32_e32 v110, s49, v103
	s_nop 0
	v_add_f32_dpp v103, v109, v109 quad_perm:[1,0,3,2] row_mask:0xf bank_mask:0xf bound_ctrl:1
	s_nop 1
	v_add_f32_dpp v103, v103, v103 quad_perm:[2,3,0,1] row_mask:0xf bank_mask:0xf bound_ctrl:1
	s_nop 1
	v_add_f32_dpp v103, v103, v103 row_half_mirror row_mask:0xf bank_mask:0xf bound_ctrl:1
	s_nop 1
	v_add_f32_dpp v103, v103, v103 row_mirror row_mask:0xf bank_mask:0xf bound_ctrl:1
	s_nop 0
	v_readlane_b32 s48, v103, 0
	v_readlane_b32 s0, v103, 16
	v_readlane_b32 s49, v103, 32
	v_readlane_b32 s50, v103, 48
	v_add_f32_dpp v103, v111, v111 quad_perm:[1,0,3,2] row_mask:0xf bank_mask:0xf bound_ctrl:1
	v_mov_b32_e32 v112, s0
	v_mov_b32_e32 v113, s50
	v_add_f32_dpp v103, v103, v103 quad_perm:[2,3,0,1] row_mask:0xf bank_mask:0xf bound_ctrl:1
	v_pk_add_f32 v[114:115], s[48:49], v[112:113]
	s_nop 0
	v_add_f32_dpp v103, v103, v103 row_half_mirror row_mask:0xf bank_mask:0xf bound_ctrl:1
	s_nop 1
	v_add_f32_dpp v103, v103, v103 row_mirror row_mask:0xf bank_mask:0xf bound_ctrl:1
	s_nop 0
	v_readlane_b32 s48, v103, 16
	v_readlane_b32 s0, v103, 0
	v_readlane_b32 s49, v103, 32
	v_readlane_b32 s50, v103, 48
	v_mov_b32_e32 v103, s48
	v_add_f32_e32 v116, s0, v103
	v_mov_b32_e32 v103, s50
	v_add_f32_e32 v118, s49, v103
	s_nop 0
	v_add_f32_dpp v103, v117, v117 quad_perm:[1,0,3,2] row_mask:0xf bank_mask:0xf bound_ctrl:1
	s_nop 1
	v_add_f32_dpp v103, v103, v103 quad_perm:[2,3,0,1] row_mask:0xf bank_mask:0xf bound_ctrl:1
	s_nop 1
	v_add_f32_dpp v103, v103, v103 row_half_mirror row_mask:0xf bank_mask:0xf bound_ctrl:1
	s_nop 1
	v_add_f32_dpp v103, v103, v103 row_mirror row_mask:0xf bank_mask:0xf bound_ctrl:1
	s_nop 0
	v_readlane_b32 s48, v103, 0
	v_readlane_b32 s0, v103, 16
	v_readlane_b32 s49, v103, 32
	v_readlane_b32 s50, v103, 48
	v_add_f32_dpp v103, v119, v119 quad_perm:[1,0,3,2] row_mask:0xf bank_mask:0xf bound_ctrl:1
	v_mov_b32_e32 v112, s0
	v_mov_b32_e32 v113, s50
	v_add_f32_dpp v103, v103, v103 quad_perm:[2,3,0,1] row_mask:0xf bank_mask:0xf bound_ctrl:1
	v_pk_add_f32 v[122:123], s[48:49], v[112:113]
	s_nop 0
	v_add_f32_dpp v103, v103, v103 row_half_mirror row_mask:0xf bank_mask:0xf bound_ctrl:1
	s_nop 1
	v_add_f32_dpp v103, v103, v103 row_mirror row_mask:0xf bank_mask:0xf bound_ctrl:1
	s_nop 0
	v_readlane_b32 s0, v103, 0
	v_readlane_b32 s48, v103, 16
	v_readlane_b32 s49, v103, 32
	v_readlane_b32 s50, v103, 48
	v_mov_b32_e32 v103, v96
	v_pk_add_f32 v[96:97], v[102:103], v[104:105]
	v_mov_b32_e32 v103, s48
	v_pk_mul_f32 v[96:97], v[96:97], s[16:17] op_sel_hi:[1,0]
	v_add_f32_e32 v124, s0, v103
	v_fma_f32 v102, -v97, v97, v96
	v_max_f32_e32 v102, 0, v102
	v_add_f32_e32 v102, 0x358637bd, v102
	v_rsq_f32_e32 v102, v102
	v_mov_b32_e32 v103, s50
	v_add_f32_e32 v126, s49, v103
	s_mov_b64 s[48:49], 0x400
	s_waitcnt vmcnt(2)
	v_pk_mul_f32 v[104:105], v[102:103], v[14:15] op_sel_hi:[0,1]
	s_waitcnt vmcnt(0)
	v_pk_fma_f32 v[112:113], v[96:97], v[104:105], v[18:19] op_sel:[1,0,0] neg_lo:[1,0,0] neg_hi:[1,0,0]
	s_nop 0
	v_pk_fma_f32 v[104:105], v[198:199], v[104:105], v[112:113]
	s_nop 0
	v_mul_f32_e32 v109, 0xbfb8aa3b, v104
	v_exp_f32_e32 v109, v109
	v_mul_f32_e32 v111, 0xbfb8aa3b, v105
	v_exp_f32_e32 v111, v111
	v_add_f32_e32 v103, 1.0, v109
	v_rcp_f32_e32 v112, v103
	v_add_f32_e32 v103, 1.0, v111
	v_pk_mul_f32 v[120:121], v[102:103], v[16:17] op_sel_hi:[0,1]
	v_pk_fma_f32 v[128:129], v[96:97], v[120:121], v[20:21] op_sel:[1,0,0] neg_lo:[1,0,0] neg_hi:[1,0,0]
	v_rcp_f32_e32 v113, v103
	v_pk_fma_f32 v[120:121], v[196:197], v[120:121], v[128:129]
	v_pk_mul_f32 v[104:105], v[104:105], v[112:113]
	v_mul_f32_e32 v109, 0xbfb8aa3b, v120
	v_exp_f32_e32 v109, v109
	v_mul_f32_e32 v111, 0xbfb8aa3b, v121
	v_exp_f32_e32 v111, v111
	v_add_f32_e32 v103, 1.0, v109
	v_rcp_f32_e32 v128, v103
	v_add_f32_e32 v103, 1.0, v111
	v_pk_mul_f32 v[130:131], v[102:103], v[6:7] op_sel_hi:[0,1]
	v_pk_fma_f32 v[132:133], v[96:97], v[130:131], v[10:11] op_sel:[1,0,0] neg_lo:[1,0,0] neg_hi:[1,0,0]
	v_rcp_f32_e32 v129, v103
	v_pk_fma_f32 v[130:131], v[194:195], v[130:131], v[132:133]
	s_nop 0
	v_mul_f32_e32 v109, 0xbfb8aa3b, v130
	v_exp_f32_e32 v109, v109
	v_mul_f32_e32 v111, 0xbfb8aa3b, v131
	v_exp_f32_e32 v111, v111
	v_add_f32_e32 v103, 1.0, v109
	v_rcp_f32_e32 v132, v103
	v_add_f32_e32 v103, 1.0, v111
	v_rcp_f32_e32 v133, v103
	v_pk_mul_f32 v[102:103], v[102:103], v[8:9] op_sel_hi:[0,1]
	v_pk_fma_f32 v[96:97], v[96:97], v[102:103], v[12:13] op_sel:[1,0,0] neg_lo:[1,0,0] neg_hi:[1,0,0]
	v_mov_b32_e32 v111, v107
	v_pk_fma_f32 v[136:137], v[192:193], v[102:103], v[96:97]
	v_pk_mul_f32 v[102:103], v[120:121], v[128:129]
	v_mul_f32_e32 v96, 0xbfb8aa3b, v136
	v_exp_f32_e32 v109, v96
	v_pk_mul_f32 v[96:97], v[130:131], v[132:133]
	v_add_f32_e32 v112, 1.0, v109
	v_mul_f32_e32 v109, 0xbfb8aa3b, v137
	v_exp_f32_e32 v113, v109
	v_mov_b32_e32 v109, v106
	v_pk_add_f32 v[106:107], v[108:109], v[110:111]
	v_rcp_f32_e32 v110, v112
	v_pk_mul_f32 v[106:107], v[106:107], s[16:17] op_sel_hi:[1,0]
	v_add_f32_e32 v109, 1.0, v113
	v_fma_f32 v108, -v107, v107, v106
	v_max_f32_e32 v108, 0, v108
	v_add_f32_e32 v108, 0x358637bd, v108
	v_rsq_f32_e32 v108, v108
	v_rcp_f32_e32 v111, v109
	v_pk_mul_f32 v[112:113], v[108:109], v[14:15] op_sel_hi:[0,1]
	v_pk_fma_f32 v[120:121], v[106:107], v[112:113], v[18:19] op_sel:[1,0,0] neg_lo:[1,0,0] neg_hi:[1,0,0]
	v_pk_mul_f32 v[110:111], v[136:137], v[110:111]
	v_pk_fma_f32 v[112:113], v[190:191], v[112:113], v[120:121]
	s_nop 0
	v_mul_f32_e32 v109, 0xbfb8aa3b, v112
	v_exp_f32_e32 v109, v109
	v_mul_f32_e32 v117, 0xbfb8aa3b, v113
	v_exp_f32_e32 v117, v117
	v_add_f32_e32 v109, 1.0, v109
	v_rcp_f32_e32 v120, v109
	v_add_f32_e32 v109, 1.0, v117
	v_pk_mul_f32 v[128:129], v[108:109], v[16:17] op_sel_hi:[0,1]
	v_pk_fma_f32 v[130:131], v[106:107], v[128:129], v[20:21] op_sel:[1,0,0] neg_lo:[1,0,0] neg_hi:[1,0,0]
	v_rcp_f32_e32 v121, v109
	v_pk_fma_f32 v[128:129], v[188:189], v[128:129], v[130:131]
	v_pk_mul_f32 v[112:113], v[112:113], v[120:121]
	v_mul_f32_e32 v117, 0xbfb8aa3b, v128
	v_exp_f32_e32 v117, v117
	v_mul_f32_e32 v119, 0xbfb8aa3b, v129
	v_exp_f32_e32 v119, v119
	v_add_f32_e32 v109, 1.0, v117
	v_rcp_f32_e32 v130, v109
	v_add_f32_e32 v109, 1.0, v119
	v_pk_mul_f32 v[132:133], v[108:109], v[6:7] op_sel_hi:[0,1]
	v_pk_fma_f32 v[136:137], v[106:107], v[132:133], v[10:11] op_sel:[1,0,0] neg_lo:[1,0,0] neg_hi:[1,0,0]
	v_rcp_f32_e32 v131, v109
	v_pk_fma_f32 v[132:133], v[186:187], v[132:133], v[136:137]
	s_nop 0
	v_mul_f32_e32 v117, 0xbfb8aa3b, v132
	v_exp_f32_e32 v117, v117
	v_mul_f32_e32 v119, 0xbfb8aa3b, v133
	v_exp_f32_e32 v119, v119
	v_add_f32_e32 v109, 1.0, v117
	v_rcp_f32_e32 v136, v109
	v_add_f32_e32 v109, 1.0, v119
	v_rcp_f32_e32 v137, v109
	v_pk_mul_f32 v[108:109], v[108:109], v[8:9] op_sel_hi:[0,1]
	v_pk_fma_f32 v[106:107], v[106:107], v[108:109], v[12:13] op_sel:[1,0,0] neg_lo:[1,0,0] neg_hi:[1,0,0]
	v_mov_b32_e32 v119, v115
	v_pk_fma_f32 v[184:185], v[184:185], v[108:109], v[106:107]
	v_pk_mul_f32 v[108:109], v[128:129], v[130:131]
	v_mul_f32_e32 v106, 0xbfb8aa3b, v184
	v_exp_f32_e32 v117, v106
	v_pk_mul_f32 v[106:107], v[132:133], v[136:137]
	v_add_f32_e32 v120, 1.0, v117
	v_mul_f32_e32 v117, 0xbfb8aa3b, v185
	v_exp_f32_e32 v121, v117
	v_mov_b32_e32 v117, v114
	v_pk_add_f32 v[114:115], v[116:117], v[118:119]
	v_rcp_f32_e32 v118, v120
	v_pk_mul_f32 v[114:115], v[114:115], s[16:17] op_sel_hi:[1,0]
	v_add_f32_e32 v117, 1.0, v121
	v_fma_f32 v116, -v115, v115, v114
	v_max_f32_e32 v116, 0, v116
	v_add_f32_e32 v116, 0x358637bd, v116
	v_rsq_f32_e32 v116, v116
	v_rcp_f32_e32 v119, v117
	v_pk_mul_f32 v[120:121], v[116:117], v[14:15] op_sel_hi:[0,1]
	v_pk_fma_f32 v[128:129], v[114:115], v[120:121], v[18:19] op_sel:[1,0,0] neg_lo:[1,0,0] neg_hi:[1,0,0]
	s_nop 0
	v_pk_fma_f32 v[128:129], v[202:203], v[120:121], v[128:129]
	s_nop 0
	v_mul_f32_e32 v117, 0xbfb8aa3b, v128
	v_exp_f32_e32 v117, v117
	v_mul_f32_e32 v120, 0xbfb8aa3b, v129
	v_exp_f32_e32 v125, v120
	v_pk_mul_f32 v[120:121], v[184:185], v[118:119]
	v_add_f32_e32 v117, 1.0, v117
	v_rcp_f32_e32 v118, v117
	v_add_f32_e32 v117, 1.0, v125
	v_pk_mul_f32 v[130:131], v[116:117], v[16:17] op_sel_hi:[0,1]
	v_pk_fma_f32 v[132:133], v[114:115], v[130:131], v[20:21] op_sel:[1,0,0] neg_lo:[1,0,0] neg_hi:[1,0,0]
	s_nop 0
	v_pk_fma_f32 v[130:131], v[200:201], v[130:131], v[132:133]
	s_nop 0
	v_mul_f32_e32 v119, 0xbfb8aa3b, v130
	v_exp_f32_e32 v125, v119
	v_mul_f32_e32 v119, 0xbfb8aa3b, v131
	v_exp_f32_e32 v127, v119
	v_rcp_f32_e32 v119, v117
	v_add_f32_e32 v117, 1.0, v125
	v_rcp_f32_e32 v132, v117
	v_add_f32_e32 v117, 1.0, v127
	v_pk_mul_f32 v[136:137], v[116:117], v[6:7] op_sel_hi:[0,1]
	v_pk_fma_f32 v[184:185], v[114:115], v[136:137], v[10:11] op_sel:[1,0,0] neg_lo:[1,0,0] neg_hi:[1,0,0]
	v_rcp_f32_e32 v133, v117
	v_pk_fma_f32 v[136:137], v[140:141], v[136:137], v[184:185]
	v_pk_mul_f32 v[118:119], v[128:129], v[118:119]
	v_mul_f32_e32 v125, 0xbfb8aa3b, v136
	v_exp_f32_e32 v125, v125
	v_mul_f32_e32 v127, 0xbfb8aa3b, v137
	v_exp_f32_e32 v127, v127
	v_add_f32_e32 v117, 1.0, v125
	v_rcp_f32_e32 v140, v117
	v_add_f32_e32 v117, 1.0, v127
	v_rcp_f32_e32 v141, v117
	v_pk_mul_f32 v[116:117], v[116:117], v[8:9] op_sel_hi:[0,1]
	v_pk_fma_f32 v[114:115], v[114:115], v[116:117], v[12:13] op_sel:[1,0,0] neg_lo:[1,0,0] neg_hi:[1,0,0]
	v_mov_b32_e32 v127, v123
	v_pk_fma_f32 v[138:139], v[138:139], v[116:117], v[114:115]
	v_pk_mul_f32 v[116:117], v[130:131], v[132:133]
	v_mul_f32_e32 v114, 0xbfb8aa3b, v138
	v_exp_f32_e32 v125, v114
	v_pk_mul_f32 v[130:131], v[92:93], v[92:93]
	v_pk_mul_f32 v[114:115], v[136:137], v[140:141]
	v_pk_fma_f32 v[130:131], v[90:91], v[90:91], v[130:131]
	v_add_f32_e32 v128, 1.0, v125
	v_mul_f32_e32 v125, 0xbfb8aa3b, v139
	v_exp_f32_e32 v129, v125
	v_mov_b32_e32 v125, v122
	v_pk_add_f32 v[122:123], v[124:125], v[126:127]
	s_nop 0
	v_pk_mul_f32 v[124:125], v[122:123], s[16:17] op_sel_hi:[1,0]
	v_add_f32_e32 v123, 1.0, v129
	v_fma_f32 v122, -v125, v125, v124
	v_max_f32_e32 v122, 0, v122
	v_add_f32_e32 v122, 0x358637bd, v122
	v_rsq_f32_e32 v126, v122
	v_rcp_f32_e32 v122, v128
	v_pk_mul_f32 v[128:129], v[110:111], v[110:111]
	v_rcp_f32_e32 v123, v123
	v_pk_mul_f32 v[14:15], v[14:15], v[126:127] op_sel_hi:[1,0]
	v_pk_mul_f32 v[6:7], v[6:7], v[126:127] op_sel_hi:[1,0]
	v_pk_fma_f32 v[18:19], v[124:125], v[14:15], v[18:19] op_sel:[1,0,0] neg_lo:[1,0,0] neg_hi:[1,0,0]
	v_pk_fma_f32 v[10:11], v[124:125], v[6:7], v[10:11] op_sel:[1,0,0] neg_lo:[1,0,0] neg_hi:[1,0,0]
	v_pk_fma_f32 v[14:15], v[134:135], v[14:15], v[18:19]
	v_pk_mul_f32 v[16:17], v[16:17], v[126:127] op_sel_hi:[1,0]
	v_mul_f32_e32 v18, 0xbfb8aa3b, v14
	v_mul_f32_e32 v19, 0xbfb8aa3b, v15
	v_exp_f32_e32 v18, v18
	v_exp_f32_e32 v19, v19
	v_pk_fma_f32 v[6:7], v[98:99], v[6:7], v[10:11]
	v_pk_fma_f32 v[20:21], v[124:125], v[16:17], v[20:21] op_sel:[1,0,0] neg_lo:[1,0,0] neg_hi:[1,0,0]
	v_mul_f32_e32 v10, 0xbfb8aa3b, v6
	v_mul_f32_e32 v11, 0xbfb8aa3b, v7
	v_pk_fma_f32 v[16:17], v[100:101], v[16:17], v[20:21]
	v_exp_f32_e32 v10, v10
	v_exp_f32_e32 v11, v11
	v_add_f32_e32 v18, 1.0, v18
	v_add_f32_e32 v19, 1.0, v19
	v_mul_f32_e32 v20, 0xbfb8aa3b, v16
	v_mul_f32_e32 v21, 0xbfb8aa3b, v17
	v_pk_mul_f32 v[8:9], v[8:9], v[126:127] op_sel_hi:[1,0]
	v_rcp_f32_e32 v18, v18
	v_rcp_f32_e32 v19, v19
	v_exp_f32_e32 v20, v20
	v_exp_f32_e32 v21, v21
	v_pk_fma_f32 v[12:13], v[124:125], v[8:9], v[12:13] op_sel:[1,0,0] neg_lo:[1,0,0] neg_hi:[1,0,0]
	v_add_f32_e32 v10, 1.0, v10
	v_pk_fma_f32 v[124:125], v[94:95], v[8:9], v[12:13]
	v_add_f32_e32 v11, 1.0, v11
	v_mul_f32_e32 v8, 0xbfb8aa3b, v124
	v_rcp_f32_e32 v10, v10
	v_rcp_f32_e32 v11, v11
	v_exp_f32_e32 v8, v8
	v_mul_f32_e32 v9, 0xbfb8aa3b, v125
	v_pk_mul_f32 v[100:101], v[14:15], v[18:19]
	v_add_f32_e32 v14, 1.0, v20
	v_add_f32_e32 v15, 1.0, v21
	v_exp_f32_e32 v9, v9
	v_rcp_f32_e32 v14, v14
	v_rcp_f32_e32 v15, v15
	v_pk_mul_f32 v[94:95], v[6:7], v[10:11]
	v_add_f32_e32 v6, 1.0, v8
	v_rcp_f32_e32 v126, v6
	v_add_f32_e32 v6, 1.0, v9
	v_pk_mul_f32 v[98:99], v[16:17], v[14:15]
	v_rcp_f32_e32 v127, v6
	global_load_dwordx4 v[6:9], v[158:159], off offset:2064
	global_load_dwordx4 v[14:17], v[158:159], off offset:2048
	global_load_dwordx4 v[10:13], v[158:159], off offset:16
	global_load_dwordx4 v[18:21], v[158:159], off
	v_pk_fma_f32 v[128:129], v[96:97], v[96:97], v[128:129]
	v_pk_mul_f32 v[122:123], v[138:139], v[122:123]
	v_pk_mul_f32 v[124:125], v[124:125], v[126:127]
	v_pk_mul_f32 v[126:127], v[102:103], v[102:103]
	s_nop 0
	v_pk_fma_f32 v[126:127], v[104:105], v[104:105], v[126:127]
	s_nop 0
	v_pk_add_f32 v[126:127], v[126:127], v[128:129]
	v_pk_mul_f32 v[128:129], v[88:89], v[88:89]
	v_add_f32_e32 v132, v126, v127
	v_pk_fma_f32 v[128:129], v[42:43], v[42:43], v[128:129]
	v_pk_mul_f32 v[126:127], v[108:109], v[108:109]
	v_pk_add_f32 v[128:129], v[128:129], v[130:131]
	v_pk_fma_f32 v[126:127], v[112:113], v[112:113], v[126:127]
	v_add_f32_e32 v133, v128, v129
	v_pk_mul_f32 v[128:129], v[120:121], v[120:121]
	v_pk_mul_f32 v[130:131], v[86:87], v[86:87]
	v_pk_fma_f32 v[128:129], v[106:107], v[106:107], v[128:129]
	v_pk_fma_f32 v[130:131], v[44:45], v[44:45], v[130:131]
	v_pk_add_f32 v[126:127], v[126:127], v[128:129]
	v_pk_mul_f32 v[128:129], v[40:41], v[40:41]
	v_add_f32_e32 v134, v126, v127
	v_pk_fma_f32 v[128:129], v[38:39], v[38:39], v[128:129]
	v_pk_mul_f32 v[126:127], v[116:117], v[116:117]
	v_pk_add_f32 v[128:129], v[128:129], v[130:131]
	v_pk_fma_f32 v[126:127], v[118:119], v[118:119], v[126:127]
	v_add_f32_e32 v135, v128, v129
	v_pk_mul_f32 v[128:129], v[122:123], v[122:123]
	v_pk_mul_f32 v[130:131], v[36:37], v[36:37]
	v_pk_fma_f32 v[128:129], v[114:115], v[114:115], v[128:129]
	v_pk_fma_f32 v[130:131], v[34:35], v[34:35], v[130:131]
	v_pk_add_f32 v[126:127], v[126:127], v[128:129]
	v_pk_mul_f32 v[128:129], v[32:33], v[32:33]
	v_add_f32_e32 v136, v126, v127
	v_pk_fma_f32 v[128:129], v[30:31], v[30:31], v[128:129]
	v_pk_mul_f32 v[126:127], v[98:99], v[98:99]
	v_pk_add_f32 v[128:129], v[128:129], v[130:131]
	v_pk_fma_f32 v[126:127], v[100:101], v[100:101], v[126:127]
	v_add_f32_e32 v137, v128, v129
	v_pk_mul_f32 v[128:129], v[124:125], v[124:125]
	v_pk_mul_f32 v[130:131], v[28:29], v[28:29]
	v_pk_fma_f32 v[128:129], v[94:95], v[94:95], v[128:129]
	v_pk_fma_f32 v[130:131], v[26:27], v[26:27], v[130:131]
	v_pk_add_f32 v[126:127], v[126:127], v[128:129]
	v_pk_mul_f32 v[128:129], v[24:25], v[24:25]
	v_add_f32_e32 v126, v126, v127
	v_pk_fma_f32 v[128:129], v[22:23], v[22:23], v[128:129]
	s_nop 0
	v_pk_add_f32 v[128:129], v[128:129], v[130:131]
	v_add_f32_dpp v130, v134, v134 quad_perm:[1,0,3,2] row_mask:0xf bank_mask:0xf bound_ctrl:1
	v_add_f32_e32 v127, v128, v129
	v_add_f32_dpp v128, v132, v132 quad_perm:[1,0,3,2] row_mask:0xf bank_mask:0xf bound_ctrl:1
	v_add_f32_dpp v126, v126, v126 quad_perm:[1,0,3,2] row_mask:0xf bank_mask:0xf bound_ctrl:1
	v_add_f32_dpp v129, v133, v133 quad_perm:[1,0,3,2] row_mask:0xf bank_mask:0xf bound_ctrl:1
	v_add_f32_dpp v128, v128, v128 quad_perm:[2,3,0,1] row_mask:0xf bank_mask:0xf bound_ctrl:1
	v_add_f32_dpp v130, v130, v130 quad_perm:[2,3,0,1] row_mask:0xf bank_mask:0xf bound_ctrl:1
	v_add_f32_dpp v126, v126, v126 quad_perm:[2,3,0,1] row_mask:0xf bank_mask:0xf bound_ctrl:1
	v_add_f32_dpp v128, v128, v128 row_half_mirror row_mask:0xf bank_mask:0xf bound_ctrl:1
	v_add_f32_dpp v129, v129, v129 quad_perm:[2,3,0,1] row_mask:0xf bank_mask:0xf bound_ctrl:1
	v_add_f32_dpp v134, v130, v130 row_half_mirror row_mask:0xf bank_mask:0xf bound_ctrl:1
	v_add_f32_dpp v130, v135, v135 quad_perm:[1,0,3,2] row_mask:0xf bank_mask:0xf bound_ctrl:1
	v_add_f32_dpp v138, v126, v126 row_half_mirror row_mask:0xf bank_mask:0xf bound_ctrl:1
	v_add_f32_dpp v126, v127, v127 quad_perm:[1,0,3,2] row_mask:0xf bank_mask:0xf bound_ctrl:1
	v_add_f32_dpp v129, v129, v129 row_half_mirror row_mask:0xf bank_mask:0xf bound_ctrl:1
	v_add_f32_dpp v130, v130, v130 quad_perm:[2,3,0,1] row_mask:0xf bank_mask:0xf bound_ctrl:1
	v_add_f32_dpp v127, v126, v126 quad_perm:[2,3,0,1] row_mask:0xf bank_mask:0xf bound_ctrl:1
	v_fmamk_f32 v126, v128, 0x3c800000, v234
	v_add_f32_dpp v135, v130, v130 row_half_mirror row_mask:0xf bank_mask:0xf bound_ctrl:1
	v_add_f32_dpp v130, v136, v136 quad_perm:[1,0,3,2] row_mask:0xf bank_mask:0xf bound_ctrl:1
	v_rsq_f32_e32 v126, v126
	v_fmamk_f32 v128, v129, 0x3c800000, v234
	v_add_f32_dpp v130, v130, v130 quad_perm:[2,3,0,1] row_mask:0xf bank_mask:0xf bound_ctrl:1
	v_rsq_f32_e32 v128, v128
	v_add_f32_dpp v127, v127, v127 row_half_mirror row_mask:0xf bank_mask:0xf bound_ctrl:1
	v_add_f32_dpp v136, v130, v130 row_half_mirror row_mask:0xf bank_mask:0xf bound_ctrl:1
	v_add_f32_dpp v130, v137, v137 quad_perm:[1,0,3,2] row_mask:0xf bank_mask:0xf bound_ctrl:1
	s_nop 1
	v_add_f32_dpp v130, v130, v130 quad_perm:[2,3,0,1] row_mask:0xf bank_mask:0xf bound_ctrl:1
	s_nop 1
	v_add_f32_dpp v137, v130, v130 row_half_mirror row_mask:0xf bank_mask:0xf bound_ctrl:1
	s_waitcnt vmcnt(2)
	v_pk_mul_f32 v[130:131], v[126:127], v[14:15] op_sel_hi:[0,1]
	v_pk_mul_f32 v[104:105], v[104:105], v[130:131]
	s_waitcnt vmcnt(0)
	v_pk_mul_f32 v[130:131], v[128:129], v[18:19] op_sel_hi:[0,1]
	v_pk_mul_f32 v[42:43], v[42:43], v[130:131]
	v_pk_mul_f32 v[130:131], v[126:127], v[16:17] op_sel_hi:[0,1]
	v_pk_mul_f32 v[102:103], v[102:103], v[130:131]
	v_pk_mul_f32 v[130:131], v[128:129], v[20:21] op_sel_hi:[0,1]
	v_pk_mul_f32 v[130:131], v[88:89], v[130:131]
	v_pk_mul_f32 v[88:89], v[126:127], v[6:7] op_sel_hi:[0,1]
	v_pk_mul_f32 v[96:97], v[96:97], v[88:89]
	v_pk_mul_f32 v[88:89], v[128:129], v[10:11] op_sel_hi:[0,1]
	v_pk_mul_f32 v[132:133], v[90:91], v[88:89]
	v_pk_mul_f32 v[88:89], v[126:127], v[8:9] op_sel_hi:[0,1]
	v_pk_mul_f32 v[110:111], v[110:111], v[88:89]
	v_pk_mul_f32 v[88:89], v[128:129], v[12:13] op_sel_hi:[0,1]
	v_pk_mul_f32 v[92:93], v[92:93], v[88:89]
	v_cvt_pk_bf16_f32 v88, v104, v105
	v_cvt_pk_bf16_f32 v89, v102, v103
	v_cvt_pk_bf16_f32 v90, v96, v97
	v_cvt_pk_bf16_f32 v91, v110, v111
	v_cvt_pk_bf16_f32 v102, v42, v43
	v_lshl_add_u64 v[42:43], v[182:183], 0, s[48:49]
	v_cvt_pk_bf16_f32 v103, v130, v131
	v_cvt_pk_bf16_f32 v104, v132, v133
	v_cvt_pk_bf16_f32 v105, v92, v93
	global_store_dwordx4 v[42:43], v[88:91], off
	s_nop 1
	v_fmamk_f32 v43, v135, 0x3c800000, v234
	v_fmamk_f32 v42, v134, 0x3c800000, v234
	v_rsq_f32_e32 v88, v43
	v_rsq_f32_e32 v42, v42
	global_store_dwordx4 v[182:183], v[102:105], off
	s_nop 1
	s_mov_b64 s[48:49], 0xc00
	v_pk_mul_f32 v[92:93], v[88:89], v[18:19] op_sel_hi:[0,1]
	v_pk_mul_f32 v[92:93], v[38:39], v[92:93]
	v_pk_mul_f32 v[38:39], v[42:43], v[16:17] op_sel_hi:[0,1]
	v_pk_mul_f32 v[96:97], v[108:109], v[38:39]
	v_pk_mul_f32 v[38:39], v[88:89], v[20:21] op_sel_hi:[0,1]
	v_pk_mul_f32 v[102:103], v[40:41], v[38:39]
	v_pk_mul_f32 v[38:39], v[42:43], v[6:7] op_sel_hi:[0,1]
	v_pk_mul_f32 v[40:41], v[106:107], v[38:39]
	v_pk_mul_f32 v[38:39], v[88:89], v[10:11] op_sel_hi:[0,1]
	v_pk_mul_f32 v[44:45], v[44:45], v[38:39]
	v_pk_mul_f32 v[38:39], v[42:43], v[8:9] op_sel_hi:[0,1]
	v_pk_mul_f32 v[90:91], v[42:43], v[14:15] op_sel_hi:[0,1]
	v_pk_mul_f32 v[42:43], v[120:121], v[38:39]
	v_pk_mul_f32 v[38:39], v[88:89], v[12:13] op_sel_hi:[0,1]
	v_pk_mul_f32 v[90:91], v[112:113], v[90:91]
	v_pk_mul_f32 v[86:87], v[86:87], v[38:39]
	v_cvt_pk_bf16_f32 v38, v90, v91
	v_cvt_pk_bf16_f32 v39, v96, v97
	v_cvt_pk_bf16_f32 v40, v40, v41
	v_cvt_pk_bf16_f32 v41, v42, v43
	v_cvt_pk_bf16_f32 v42, v92, v93
	v_cvt_pk_bf16_f32 v43, v102, v103
	v_cvt_pk_bf16_f32 v44, v44, v45
	s_nop 0
	v_cvt_pk_bf16_f32 v45, v86, v87
	v_lshl_add_u64 v[88:89], v[182:183], 0, s[48:49]
	global_store_dwordx4 v[88:89], v[38:41], off
	s_nop 1
	v_fmamk_f32 v39, v137, 0x3c800000, v234
	v_fmamk_f32 v38, v136, 0x3c800000, v234
	v_rsq_f32_e32 v40, v39
	v_rsq_f32_e32 v38, v38
	v_lshl_add_u64 v[86:87], v[182:183], 0, s[14:15]
	global_store_dwordx4 v[86:87], v[42:45], off
	s_nop 1
	v_pk_mul_f32 v[44:45], v[40:41], v[18:19] op_sel_hi:[0,1]
	v_pk_mul_f32 v[44:45], v[30:31], v[44:45]
	v_pk_mul_f32 v[30:31], v[38:39], v[16:17] op_sel_hi:[0,1]
	v_pk_mul_f32 v[86:87], v[116:117], v[30:31]
	v_pk_mul_f32 v[30:31], v[40:41], v[20:21] op_sel_hi:[0,1]
	v_pk_mul_f32 v[88:89], v[32:33], v[30:31]
	v_pk_mul_f32 v[30:31], v[38:39], v[6:7] op_sel_hi:[0,1]
	v_pk_mul_f32 v[32:33], v[114:115], v[30:31]
	v_pk_mul_f32 v[30:31], v[40:41], v[10:11] op_sel_hi:[0,1]
	v_pk_mul_f32 v[90:91], v[34:35], v[30:31]
	v_pk_mul_f32 v[30:31], v[38:39], v[8:9] op_sel_hi:[0,1]
	v_pk_mul_f32 v[42:43], v[38:39], v[14:15] op_sel_hi:[0,1]
	v_pk_mul_f32 v[34:35], v[122:123], v[30:31]
	v_pk_mul_f32 v[30:31], v[40:41], v[12:13] op_sel_hi:[0,1]
	v_pk_mul_f32 v[42:43], v[118:119], v[42:43]
	v_pk_mul_f32 v[38:39], v[36:37], v[30:31]
	v_cvt_pk_bf16_f32 v30, v42, v43
	v_cvt_pk_bf16_f32 v31, v86, v87
	v_cvt_pk_bf16_f32 v32, v32, v33
	v_cvt_pk_bf16_f32 v33, v34, v35
	v_cvt_pk_bf16_f32 v34, v44, v45
	v_cvt_pk_bf16_f32 v35, v88, v89
	v_cvt_pk_bf16_f32 v36, v90, v91
	s_nop 0
	v_cvt_pk_bf16_f32 v37, v38, v39
	v_lshl_add_u64 v[40:41], v[182:183], 0, s[18:19]
	global_store_dwordx4 v[40:41], v[30:33], off
	s_nop 1
	v_fmamk_f32 v30, v138, 0x3c800000, v234
	v_fmamk_f32 v31, v127, 0x3c800000, v234
	v_rsq_f32_e32 v30, v30
	v_rsq_f32_e32 v32, v31
	v_lshl_add_u64 v[38:39], v[182:183], 0, s[12:13]
	global_store_dwordx4 v[38:39], v[34:37], off
	s_nop 1
	v_pk_mul_f32 v[6:7], v[6:7], v[30:31] op_sel_hi:[1,0]
	v_pk_mul_f32 v[18:19], v[18:19], v[32:33] op_sel_hi:[1,0]
	v_pk_mul_f32 v[20:21], v[20:21], v[32:33] op_sel_hi:[1,0]
	v_pk_mul_f32 v[18:19], v[22:23], v[18:19]
	v_pk_mul_f32 v[22:23], v[94:95], v[6:7]
	v_pk_mul_f32 v[6:7], v[10:11], v[32:33] op_sel_hi:[1,0]
	v_pk_mul_f32 v[16:17], v[16:17], v[30:31] op_sel_hi:[1,0]
	v_pk_mul_f32 v[20:21], v[24:25], v[20:21]
	v_pk_mul_f32 v[24:25], v[26:27], v[6:7]
	v_pk_mul_f32 v[6:7], v[8:9], v[30:31] op_sel_hi:[1,0]
	v_pk_mul_f32 v[14:15], v[14:15], v[30:31] op_sel_hi:[1,0]
	v_pk_mul_f32 v[16:17], v[98:99], v[16:17]
	v_pk_mul_f32 v[10:11], v[124:125], v[6:7]
	v_pk_mul_f32 v[6:7], v[12:13], v[32:33] op_sel_hi:[1,0]
	v_pk_mul_f32 v[14:15], v[100:101], v[14:15]
	v_pk_mul_f32 v[26:27], v[28:29], v[6:7]
	v_cvt_pk_bf16_f32 v6, v14, v15
	v_cvt_pk_bf16_f32 v7, v16, v17
	v_cvt_pk_bf16_f32 v8, v22, v23
	v_cvt_pk_bf16_f32 v9, v10, v11
	v_cvt_pk_bf16_f32 v10, v18, v19
	v_cvt_pk_bf16_f32 v11, v20, v21
	v_cvt_pk_bf16_f32 v12, v24, v25
	s_nop 0
	v_cvt_pk_bf16_f32 v13, v26, v27
	v_lshl_add_u64 v[16:17], v[182:183], 0, s[40:41]
	global_store_dwordx4 v[16:17], v[6:9], off
	s_nop 1
	v_lshl_add_u64 v[14:15], v[182:183], 0, s[36:37]
	global_store_dwordx4 v[14:15], v[10:13], off
	s_nop 1
	v_mov_b64_e32 v[18:19], v[46:47]
	v_mov_b64_e32 v[14:15], v[50:51]
	v_mov_b64_e32 v[10:11], v[54:55]
	v_mov_b64_e32 v[6:7], v[58:59]
	v_mov_b64_e32 v[42:43], v[62:63]
	v_mov_b64_e32 v[38:39], v[66:67]
	v_mov_b64_e32 v[34:35], v[70:71]
	v_mov_b64_e32 v[30:31], v[74:75]
	v_mov_b64_e32 v[26:27], v[78:79]
	v_mov_b64_e32 v[22:23], v[82:83]
	s_mov_b64 s[48:49], 0
	v_mov_b64_e32 v[20:21], v[48:49]
	v_mov_b64_e32 v[16:17], v[52:53]
	v_mov_b64_e32 v[12:13], v[56:57]
	v_mov_b64_e32 v[8:9], v[60:61]
	v_mov_b64_e32 v[44:45], v[64:65]
	v_mov_b64_e32 v[40:41], v[68:69]
	v_mov_b64_e32 v[36:37], v[72:73]
	v_mov_b64_e32 v[32:33], v[76:77]
	v_mov_b64_e32 v[28:29], v[80:81]
	v_mov_b64_e32 v[24:25], v[84:85]
	s_cbranch_vccnz .LBB0_387

.LBB0_507:
	s_and_b64 vcc, exec, s[4:5]
	s_cbranch_vccz .LBB0_544
	s_waitcnt vmcnt(0)
	s_cmp_gt_u32 s60, 63
	s_waitcnt lgkmcnt(0)
	s_barrier
	s_cbranch_scc1 .LBB0_543
	s_cmp_eq_u32 s100, 0
	s_cbranch_scc1 .Lwb_skip_fb2
	buffer_wbl2 sc1
	s_waitcnt vmcnt(0)
.Lwb_skip_fb2:
	s_add_u32 s8, s34, 0x44000
	s_addc_u32 s9, s35, 0
	s_mov_b32 s11, 0
	v_cmp_eq_u32_e64 s[4:5], 0, v1
	s_and_saveexec_b64 s[6:7], s[4:5]
	s_cbranch_execz .LBB0_511
	s_mov_b32 s10, s2
	s_lshl_b64 s[0:1], s[10:11], 2
	s_add_u32 s0, s8, s0
	s_addc_u32 s1, s9, s1
	v_mov_b32_e32 v2, 0
	v_mov_b32_e32 v3, 2
	global_store_dword v2, v3, s[0:1] sc1

.LBB0_670:
	v_add_u32_e32 v162, s40, v217
	v_ashrrev_i32_e32 v163, 31, v162
	v_lshlrev_b64 v[168:169], 10, v[162:163]
	v_lshl_add_u64 v[172:173], v[168:169], 0, v[210:211]
	v_cvt_pk_bf16_f32 v168, v126, v127
	s_waitcnt lgkmcnt(0)
	v_pk_mul_f32 v[126:127], v[126:127], v[166:167] op_sel_hi:[1,0]
	v_cvt_pk_bf16_f32 v169, v128, v129
	v_cvt_pk_bf16_f32 v170, v122, v123
	v_pk_mul_f32 v[128:129], v[128:129], v[166:167] op_sel_hi:[1,0]
	s_waitcnt vmcnt(3)
	v_pk_fma_f32 v[126:127], v[154:155], v[126:127], v[158:159]
	v_pk_mul_f32 v[122:123], v[122:123], v[166:167] op_sel_hi:[1,0]
	v_cvt_pk_bf16_f32 v171, v124, v125
	v_pk_fma_f32 v[128:129], v[156:157], v[128:129], v[160:161]
	v_pk_mul_f32 v[124:125], v[124:125], v[166:167] op_sel_hi:[1,0]
	v_pk_fma_f32 v[174:175], v[146:147], v[122:123], v[150:151]
	v_cvt_pk_bf16_f32 v122, v126, v127
	v_lshlrev_b64 v[126:127], 1, v[172:173]
	v_pk_fma_f32 v[176:177], v[148:149], v[124:125], v[152:153]
	v_cvt_pk_bf16_f32 v123, v128, v129
	v_cvt_pk_bf16_f32 v124, v174, v175
	v_lshl_add_u64 v[128:129], s[22:23], 0, v[126:127]
	v_cvt_pk_bf16_f32 v125, v176, v177
	global_store_dwordx4 v[128:129], v[168:171], off
	s_nop 1
	v_lshl_add_u64 v[126:127], s[24:25], 0, v[126:127]
	global_store_dwordx4 v[126:127], v[122:125], off
	s_nop 1
	v_cvt_pk_bf16_f32 v122, v118, v119
	v_pk_mul_f32 v[118:119], v[118:119], v[166:167] op_sel_hi:[1,0]
	v_cvt_pk_bf16_f32 v123, v120, v121
	v_cvt_pk_bf16_f32 v124, v114, v115
	v_cvt_pk_bf16_f32 v125, v116, v117
	v_pk_mul_f32 v[120:121], v[120:121], v[166:167] op_sel_hi:[1,0]
	s_waitcnt vmcnt(2)
	v_pk_fma_f32 v[118:119], v[134:135], v[118:119], v[142:143]
	v_pk_mul_f32 v[116:117], v[116:117], v[166:167] op_sel_hi:[1,0]
	v_pk_mul_f32 v[114:115], v[114:115], v[166:167] op_sel_hi:[1,0]
	s_mov_b64 s[10:11], 0x100
	v_pk_fma_f32 v[120:121], v[136:137], v[120:121], v[144:145]
	s_waitcnt vmcnt(0)
	v_pk_fma_f32 v[166:167], v[130:131], v[114:115], v[138:139]
	v_pk_fma_f32 v[168:169], v[132:133], v[116:117], v[140:141]
	v_cvt_pk_bf16_f32 v114, v118, v119
	v_cvt_pk_bf16_f32 v115, v120, v121
	v_cvt_pk_bf16_f32 v116, v166, v167
	v_lshl_add_u64 v[118:119], v[128:129], 0, s[10:11]
	v_cvt_pk_bf16_f32 v117, v168, v169
	global_store_dwordx4 v[118:119], v[122:125], off
	s_nop 1
	v_lshl_add_u64 v[118:119], v[126:127], 0, s[10:11]
	global_store_dwordx4 v[118:119], v[114:117], off
	s_nop 1
	v_cndmask_b32_e64 v114, 0, 1, s[8:9]
	v_cmp_ne_u32_e64 s[6:7], 1, v114
	s_andn2_b64 vcc, exec, s[8:9]
	s_cbranch_vccnz .LBB0_672
	ds_read_b32 v164, v165 offset:8256
.LBB0_672:
	v_add3_u32 v114, s40, v217, 16
	v_ashrrev_i32_e32 v115, 31, v114
	v_lshlrev_b64 v[114:115], 10, v[114:115]
	v_lshl_add_u64 v[118:119], v[114:115], 0, v[210:211]
	v_cvt_pk_bf16_f32 v114, v110, v111
	s_waitcnt lgkmcnt(0)
	v_pk_mul_f32 v[110:111], v[110:111], v[164:165] op_sel_hi:[1,0]
	v_cvt_pk_bf16_f32 v115, v112, v113
	v_cvt_pk_bf16_f32 v116, v106, v107
	v_cvt_pk_bf16_f32 v117, v108, v109
	v_pk_mul_f32 v[112:113], v[112:113], v[164:165] op_sel_hi:[1,0]
	v_pk_fma_f32 v[110:111], v[154:155], v[110:111], v[158:159]
	v_pk_mul_f32 v[108:109], v[108:109], v[164:165] op_sel_hi:[1,0]
	v_pk_mul_f32 v[106:107], v[106:107], v[164:165] op_sel_hi:[1,0]
	v_pk_fma_f32 v[112:113], v[156:157], v[112:113], v[160:161]
	v_pk_fma_f32 v[120:121], v[148:149], v[108:109], v[152:153]
	v_pk_fma_f32 v[108:109], v[146:147], v[106:107], v[150:151]
	v_cvt_pk_bf16_f32 v106, v110, v111
	v_lshlrev_b64 v[110:111], 1, v[118:119]
	v_cvt_pk_bf16_f32 v107, v112, v113
	v_cvt_pk_bf16_f32 v108, v108, v109
	v_cvt_pk_bf16_f32 v109, v120, v121
	v_lshl_add_u64 v[112:113], s[22:23], 0, v[110:111]
	global_store_dwordx4 v[112:113], v[114:117], off
	s_nop 1
	v_lshl_add_u64 v[110:111], s[24:25], 0, v[110:111]
	global_store_dwordx4 v[110:111], v[106:109], off
	s_nop 1
	v_cvt_pk_bf16_f32 v106, v102, v103
	v_cvt_pk_bf16_f32 v107, v104, v105
	v_cvt_pk_bf16_f32 v108, v98, v99
	v_cvt_pk_bf16_f32 v109, v100, v101
	v_pk_mul_f32 v[102:103], v[102:103], v[164:165] op_sel_hi:[1,0]
	v_pk_mul_f32 v[100:101], v[100:101], v[164:165] op_sel_hi:[1,0]
	v_pk_mul_f32 v[98:99], v[98:99], v[164:165] op_sel_hi:[1,0]
	v_pk_mul_f32 v[104:105], v[104:105], v[164:165] op_sel_hi:[1,0]
	v_pk_fma_f32 v[102:103], v[134:135], v[102:103], v[142:143]
	v_pk_fma_f32 v[114:115], v[132:133], v[100:101], v[140:141]
	v_pk_fma_f32 v[100:101], v[130:131], v[98:99], v[138:139]
	v_pk_fma_f32 v[104:105], v[136:137], v[104:105], v[144:145]
	v_cvt_pk_bf16_f32 v98, v102, v103
	v_lshl_add_u64 v[102:103], v[112:113], 0, s[10:11]
	v_cvt_pk_bf16_f32 v99, v104, v105
	v_cvt_pk_bf16_f32 v100, v100, v101
	v_cvt_pk_bf16_f32 v101, v114, v115
	global_store_dwordx4 v[102:103], v[106:109], off
	s_nop 1
	v_lshl_add_u64 v[102:103], v[110:111], 0, s[10:11]
	global_store_dwordx4 v[102:103], v[98:101], off
	s_nop 1
	v_mov_b32_e32 v98, 0x7fc00000
	s_and_b64 vcc, exec, s[6:7]
	v_mov_b32_e32 v100, 0x7fc00000
	s_cbranch_vccnz .LBB0_674
	ds_read_b32 v100, v165 offset:8320
.LBB0_674:
	v_add3_u32 v102, s40, v217, 32
	v_ashrrev_i32_e32 v103, 31, v102
	v_lshlrev_b64 v[102:103], 10, v[102:103]
	v_lshl_add_u64 v[106:107], v[102:103], 0, v[210:211]
	v_cvt_pk_bf16_f32 v102, v94, v95
	s_waitcnt lgkmcnt(0)
	v_pk_mul_f32 v[94:95], v[94:95], v[100:101] op_sel_hi:[1,0]
	v_cvt_pk_bf16_f32 v103, v96, v97
	v_cvt_pk_bf16_f32 v104, v90, v91
	v_cvt_pk_bf16_f32 v105, v92, v93
	v_pk_mul_f32 v[96:97], v[96:97], v[100:101] op_sel_hi:[1,0]
	v_pk_fma_f32 v[94:95], v[154:155], v[94:95], v[158:159]
	v_pk_mul_f32 v[92:93], v[92:93], v[100:101] op_sel_hi:[1,0]
	v_pk_mul_f32 v[90:91], v[90:91], v[100:101] op_sel_hi:[1,0]
	v_pk_fma_f32 v[96:97], v[156:157], v[96:97], v[160:161]
	v_pk_fma_f32 v[108:109], v[148:149], v[92:93], v[152:153]
	v_pk_fma_f32 v[92:93], v[146:147], v[90:91], v[150:151]
	v_cvt_pk_bf16_f32 v90, v94, v95
	v_lshlrev_b64 v[94:95], 1, v[106:107]
	v_cvt_pk_bf16_f32 v91, v96, v97
	v_cvt_pk_bf16_f32 v92, v92, v93
	v_cvt_pk_bf16_f32 v93, v108, v109
	v_lshl_add_u64 v[96:97], s[22:23], 0, v[94:95]
	global_store_dwordx4 v[96:97], v[102:105], off
	s_nop 1
	v_lshl_add_u64 v[94:95], s[24:25], 0, v[94:95]
	global_store_dwordx4 v[94:95], v[90:93], off
	s_nop 1
	v_cvt_pk_bf16_f32 v90, v86, v87
	v_cvt_pk_bf16_f32 v91, v88, v89
	v_cvt_pk_bf16_f32 v92, v82, v83
	v_cvt_pk_bf16_f32 v93, v84, v85
	v_pk_mul_f32 v[86:87], v[86:87], v[100:101] op_sel_hi:[1,0]
	v_pk_mul_f32 v[84:85], v[84:85], v[100:101] op_sel_hi:[1,0]
	v_pk_mul_f32 v[82:83], v[82:83], v[100:101] op_sel_hi:[1,0]
	v_pk_mul_f32 v[88:89], v[88:89], v[100:101] op_sel_hi:[1,0]
	v_pk_fma_f32 v[86:87], v[134:135], v[86:87], v[142:143]
	v_pk_fma_f32 v[100:101], v[132:133], v[84:85], v[140:141]
	v_pk_fma_f32 v[84:85], v[130:131], v[82:83], v[138:139]
	s_mov_b64 s[8:9], 0x100
	v_pk_fma_f32 v[88:89], v[136:137], v[88:89], v[144:145]
	v_cvt_pk_bf16_f32 v82, v86, v87
	v_lshl_add_u64 v[86:87], v[96:97], 0, s[8:9]
	v_cvt_pk_bf16_f32 v83, v88, v89
	v_cvt_pk_bf16_f32 v84, v84, v85
	v_cvt_pk_bf16_f32 v85, v100, v101
	global_store_dwordx4 v[86:87], v[90:93], off
	s_nop 1
	v_lshl_add_u64 v[86:87], v[94:95], 0, s[8:9]
	global_store_dwordx4 v[86:87], v[82:85], off
	s_nop 1
	s_and_b64 vcc, exec, s[6:7]
	s_cbranch_vccnz .LBB0_676
	ds_read_b32 v98, v165 offset:8384
.LBB0_676:
	v_add3_u32 v82, s40, v217, 48
	v_ashrrev_i32_e32 v83, 31, v82
	v_lshlrev_b64 v[82:83], 10, v[82:83]
	v_lshl_add_u64 v[86:87], v[82:83], 0, v[210:211]
	v_cvt_pk_bf16_f32 v82, v78, v79
	s_waitcnt lgkmcnt(0)
	v_pk_mul_f32 v[78:79], v[78:79], v[98:99] op_sel_hi:[1,0]
	v_cvt_pk_bf16_f32 v83, v80, v81
	v_cvt_pk_bf16_f32 v84, v74, v75
	v_cvt_pk_bf16_f32 v85, v76, v77
	v_pk_mul_f32 v[80:81], v[80:81], v[98:99] op_sel_hi:[1,0]
	v_pk_fma_f32 v[78:79], v[154:155], v[78:79], v[158:159]
	v_pk_mul_f32 v[76:77], v[76:77], v[98:99] op_sel_hi:[1,0]
	v_pk_mul_f32 v[74:75], v[74:75], v[98:99] op_sel_hi:[1,0]
	v_pk_fma_f32 v[80:81], v[156:157], v[80:81], v[160:161]
	v_pk_fma_f32 v[88:89], v[148:149], v[76:77], v[152:153]
	v_pk_fma_f32 v[76:77], v[146:147], v[74:75], v[150:151]
	v_cvt_pk_bf16_f32 v74, v78, v79
	v_lshlrev_b64 v[78:79], 1, v[86:87]
	v_cvt_pk_bf16_f32 v75, v80, v81
	v_cvt_pk_bf16_f32 v76, v76, v77
	v_cvt_pk_bf16_f32 v77, v88, v89
	v_lshl_add_u64 v[80:81], s[22:23], 0, v[78:79]
	global_store_dwordx4 v[80:81], v[82:85], off
	s_nop 1
	v_lshl_add_u64 v[78:79], s[24:25], 0, v[78:79]
	global_store_dwordx4 v[78:79], v[74:77], off
	s_nop 1
	v_cvt_pk_bf16_f32 v74, v70, v71
	v_cvt_pk_bf16_f32 v75, v72, v73
	v_cvt_pk_bf16_f32 v76, v66, v67
	v_cvt_pk_bf16_f32 v77, v68, v69
	v_pk_mul_f32 v[70:71], v[70:71], v[98:99] op_sel_hi:[1,0]
	v_pk_mul_f32 v[68:69], v[68:69], v[98:99] op_sel_hi:[1,0]
	v_pk_mul_f32 v[66:67], v[66:67], v[98:99] op_sel_hi:[1,0]
	v_pk_mul_f32 v[72:73], v[72:73], v[98:99] op_sel_hi:[1,0]
	v_pk_fma_f32 v[70:71], v[134:135], v[70:71], v[142:143]
	v_pk_fma_f32 v[82:83], v[132:133], v[68:69], v[140:141]
	v_pk_fma_f32 v[68:69], v[130:131], v[66:67], v[138:139]
	v_pk_fma_f32 v[72:73], v[136:137], v[72:73], v[144:145]
	v_cvt_pk_bf16_f32 v66, v70, v71
	v_lshl_add_u64 v[70:71], v[80:81], 0, s[8:9]
	v_cvt_pk_bf16_f32 v67, v72, v73
	v_cvt_pk_bf16_f32 v68, v68, v69
	v_cvt_pk_bf16_f32 v69, v82, v83
	global_store_dwordx4 v[70:71], v[74:77], off
	s_nop 1
	v_lshl_add_u64 v[70:71], v[78:79], 0, s[8:9]
	global_store_dwordx4 v[70:71], v[66:69], off
	s_nop 1
	v_mov_b32_e32 v66, 0x7fc00000
	s_and_b64 vcc, exec, s[6:7]
	v_mov_b32_e32 v68, 0x7fc00000
	s_cbranch_vccnz .LBB0_678
	ds_read_b32 v68, v165 offset:8704
.LBB0_678:
	v_add_u32_e32 v70, 0x80, v162
	v_ashrrev_i32_e32 v71, 31, v70
	v_lshlrev_b64 v[70:71], 10, v[70:71]
	v_lshl_add_u64 v[74:75], v[70:71], 0, v[210:211]
	v_cvt_pk_bf16_f32 v70, v62, v63
	s_waitcnt lgkmcnt(0)
	v_pk_mul_f32 v[62:63], v[62:63], v[68:69] op_sel_hi:[1,0]
	v_cvt_pk_bf16_f32 v71, v64, v65
	v_cvt_pk_bf16_f32 v72, v58, v59
	v_cvt_pk_bf16_f32 v73, v60, v61
	v_pk_mul_f32 v[64:65], v[64:65], v[68:69] op_sel_hi:[1,0]
	v_pk_fma_f32 v[62:63], v[154:155], v[62:63], v[158:159]
	v_pk_mul_f32 v[60:61], v[60:61], v[68:69] op_sel_hi:[1,0]
	v_pk_mul_f32 v[58:59], v[58:59], v[68:69] op_sel_hi:[1,0]
	v_pk_fma_f32 v[64:65], v[156:157], v[64:65], v[160:161]
	v_pk_fma_f32 v[76:77], v[148:149], v[60:61], v[152:153]
	v_pk_fma_f32 v[60:61], v[146:147], v[58:59], v[150:151]
	v_cvt_pk_bf16_f32 v58, v62, v63
	v_lshlrev_b64 v[62:63], 1, v[74:75]
	v_cvt_pk_bf16_f32 v59, v64, v65
	v_cvt_pk_bf16_f32 v60, v60, v61
	v_cvt_pk_bf16_f32 v61, v76, v77
	v_lshl_add_u64 v[64:65], s[22:23], 0, v[62:63]
	global_store_dwordx4 v[64:65], v[70:73], off
	s_nop 1
	v_lshl_add_u64 v[62:63], s[24:25], 0, v[62:63]
	global_store_dwordx4 v[62:63], v[58:61], off
	s_nop 1
	v_cvt_pk_bf16_f32 v58, v54, v55
	v_cvt_pk_bf16_f32 v59, v56, v57
	v_cvt_pk_bf16_f32 v60, v50, v51
	v_cvt_pk_bf16_f32 v61, v52, v53
	v_pk_mul_f32 v[54:55], v[54:55], v[68:69] op_sel_hi:[1,0]
	v_pk_mul_f32 v[52:53], v[52:53], v[68:69] op_sel_hi:[1,0]
	v_pk_mul_f32 v[50:51], v[50:51], v[68:69] op_sel_hi:[1,0]
	v_pk_mul_f32 v[56:57], v[56:57], v[68:69] op_sel_hi:[1,0]
	v_pk_fma_f32 v[54:55], v[134:135], v[54:55], v[142:143]
	v_pk_fma_f32 v[68:69], v[132:133], v[52:53], v[140:141]
	v_pk_fma_f32 v[52:53], v[130:131], v[50:51], v[138:139]
	v_pk_fma_f32 v[56:57], v[136:137], v[56:57], v[144:145]
	v_cvt_pk_bf16_f32 v50, v54, v55
	v_lshl_add_u64 v[54:55], v[64:65], 0, s[8:9]
	v_cvt_pk_bf16_f32 v51, v56, v57
	v_cvt_pk_bf16_f32 v52, v52, v53
	v_cvt_pk_bf16_f32 v53, v68, v69
	global_store_dwordx4 v[54:55], v[58:61], off
	s_nop 1
	v_lshl_add_u64 v[54:55], v[62:63], 0, s[8:9]
	global_store_dwordx4 v[54:55], v[50:53], off
	s_nop 1
	s_and_b64 vcc, exec, s[6:7]
	s_cbranch_vccnz .LBB0_680
	ds_read_b32 v66, v165 offset:8768
.LBB0_680:
	v_add_u32_e32 v50, 0x90, v162
	v_ashrrev_i32_e32 v51, 31, v50
	v_lshlrev_b64 v[50:51], 10, v[50:51]
	v_lshl_add_u64 v[54:55], v[50:51], 0, v[210:211]
	v_cvt_pk_bf16_f32 v50, v46, v47
	s_waitcnt lgkmcnt(0)
	v_pk_mul_f32 v[46:47], v[46:47], v[66:67] op_sel_hi:[1,0]
	v_cvt_pk_bf16_f32 v51, v48, v49
	v_cvt_pk_bf16_f32 v52, v42, v43
	v_cvt_pk_bf16_f32 v53, v44, v45
	v_pk_mul_f32 v[48:49], v[48:49], v[66:67] op_sel_hi:[1,0]
	v_pk_fma_f32 v[46:47], v[154:155], v[46:47], v[158:159]
	v_pk_mul_f32 v[44:45], v[44:45], v[66:67] op_sel_hi:[1,0]
	v_pk_mul_f32 v[42:43], v[42:43], v[66:67] op_sel_hi:[1,0]
	v_pk_fma_f32 v[48:49], v[156:157], v[48:49], v[160:161]
	v_pk_fma_f32 v[56:57], v[148:149], v[44:45], v[152:153]
	v_pk_fma_f32 v[44:45], v[146:147], v[42:43], v[150:151]
	v_cvt_pk_bf16_f32 v42, v46, v47
	v_lshlrev_b64 v[46:47], 1, v[54:55]
	v_cvt_pk_bf16_f32 v43, v48, v49
	v_cvt_pk_bf16_f32 v44, v44, v45
	v_cvt_pk_bf16_f32 v45, v56, v57
	v_lshl_add_u64 v[48:49], s[22:23], 0, v[46:47]
	global_store_dwordx4 v[48:49], v[50:53], off
	s_nop 1
	v_lshl_add_u64 v[46:47], s[24:25], 0, v[46:47]
	global_store_dwordx4 v[46:47], v[42:45], off
	s_nop 1
	v_cvt_pk_bf16_f32 v42, v38, v39
	v_cvt_pk_bf16_f32 v43, v40, v41
	v_cvt_pk_bf16_f32 v44, v34, v35
	v_cvt_pk_bf16_f32 v45, v36, v37
	v_pk_mul_f32 v[38:39], v[38:39], v[66:67] op_sel_hi:[1,0]
	v_pk_mul_f32 v[36:37], v[36:37], v[66:67] op_sel_hi:[1,0]
	v_pk_mul_f32 v[34:35], v[34:35], v[66:67] op_sel_hi:[1,0]
	v_pk_mul_f32 v[40:41], v[40:41], v[66:67] op_sel_hi:[1,0]
	v_pk_fma_f32 v[38:39], v[134:135], v[38:39], v[142:143]
	v_pk_fma_f32 v[50:51], v[132:133], v[36:37], v[140:141]
	v_pk_fma_f32 v[36:37], v[130:131], v[34:35], v[138:139]
	v_pk_fma_f32 v[40:41], v[136:137], v[40:41], v[144:145]
	v_cvt_pk_bf16_f32 v34, v38, v39
	v_lshl_add_u64 v[38:39], v[48:49], 0, s[8:9]
	v_cvt_pk_bf16_f32 v35, v40, v41
	v_cvt_pk_bf16_f32 v36, v36, v37
	v_cvt_pk_bf16_f32 v37, v50, v51
	global_store_dwordx4 v[38:39], v[42:45], off
	s_nop 1
	v_lshl_add_u64 v[38:39], v[46:47], 0, s[8:9]
	global_store_dwordx4 v[38:39], v[34:37], off
	s_nop 1
	v_mov_b32_e32 v34, 0x7fc00000
	s_and_b64 vcc, exec, s[6:7]
	v_mov_b32_e32 v36, 0x7fc00000
	s_cbranch_vccnz .LBB0_682
	ds_read_b32 v36, v165 offset:8832
.LBB0_682:
	v_add_u32_e32 v38, 0xa0, v162
	v_ashrrev_i32_e32 v39, 31, v38
	v_lshlrev_b64 v[38:39], 10, v[38:39]
	v_lshl_add_u64 v[42:43], v[38:39], 0, v[210:211]
	v_cvt_pk_bf16_f32 v38, v30, v31
	s_waitcnt lgkmcnt(0)
	v_pk_mul_f32 v[30:31], v[30:31], v[36:37] op_sel_hi:[1,0]
	v_cvt_pk_bf16_f32 v39, v32, v33
	v_cvt_pk_bf16_f32 v40, v26, v27
	v_cvt_pk_bf16_f32 v41, v28, v29
	v_pk_mul_f32 v[32:33], v[32:33], v[36:37] op_sel_hi:[1,0]
	v_pk_fma_f32 v[30:31], v[154:155], v[30:31], v[158:159]
	v_pk_mul_f32 v[28:29], v[28:29], v[36:37] op_sel_hi:[1,0]
	v_pk_mul_f32 v[26:27], v[26:27], v[36:37] op_sel_hi:[1,0]
	v_pk_fma_f32 v[32:33], v[156:157], v[32:33], v[160:161]
	v_pk_fma_f32 v[44:45], v[148:149], v[28:29], v[152:153]
	v_pk_fma_f32 v[28:29], v[146:147], v[26:27], v[150:151]
	v_cvt_pk_bf16_f32 v26, v30, v31
	v_lshlrev_b64 v[30:31], 1, v[42:43]
	v_cvt_pk_bf16_f32 v27, v32, v33
	v_cvt_pk_bf16_f32 v28, v28, v29
	v_cvt_pk_bf16_f32 v29, v44, v45
	v_lshl_add_u64 v[32:33], s[22:23], 0, v[30:31]
	global_store_dwordx4 v[32:33], v[38:41], off
	s_nop 1
	v_lshl_add_u64 v[30:31], s[24:25], 0, v[30:31]
	global_store_dwordx4 v[30:31], v[26:29], off
	s_nop 1
	v_cvt_pk_bf16_f32 v26, v22, v23
	v_cvt_pk_bf16_f32 v27, v24, v25
	v_cvt_pk_bf16_f32 v28, v18, v19
	v_cvt_pk_bf16_f32 v29, v20, v21
	v_pk_mul_f32 v[22:23], v[22:23], v[36:37] op_sel_hi:[1,0]
	v_pk_mul_f32 v[20:21], v[20:21], v[36:37] op_sel_hi:[1,0]
	v_pk_mul_f32 v[18:19], v[18:19], v[36:37] op_sel_hi:[1,0]
	v_pk_mul_f32 v[24:25], v[24:25], v[36:37] op_sel_hi:[1,0]
	v_pk_fma_f32 v[22:23], v[134:135], v[22:23], v[142:143]
	v_pk_fma_f32 v[36:37], v[132:133], v[20:21], v[140:141]
	v_pk_fma_f32 v[20:21], v[130:131], v[18:19], v[138:139]
	v_pk_fma_f32 v[24:25], v[136:137], v[24:25], v[144:145]
	v_cvt_pk_bf16_f32 v18, v22, v23
	v_lshl_add_u64 v[22:23], v[32:33], 0, s[8:9]
	v_cvt_pk_bf16_f32 v19, v24, v25
	v_cvt_pk_bf16_f32 v20, v20, v21
	v_cvt_pk_bf16_f32 v21, v36, v37
	global_store_dwordx4 v[22:23], v[26:29], off
	s_nop 1
	v_lshl_add_u64 v[22:23], v[30:31], 0, s[8:9]
	global_store_dwordx4 v[22:23], v[18:21], off
	s_nop 1
	s_and_b64 vcc, exec, s[6:7]
	s_cbranch_vccnz .LBB0_684
	ds_read_b32 v34, v165 offset:8896
.LBB0_684:
	v_add_u32_e32 v18, 0xb0, v162
	v_ashrrev_i32_e32 v19, 31, v18
	v_lshlrev_b64 v[18:19], 10, v[18:19]
	v_lshl_add_u64 v[22:23], v[18:19], 0, v[210:211]
	v_cvt_pk_bf16_f32 v18, v14, v15
	s_waitcnt lgkmcnt(0)
	v_pk_mul_f32 v[14:15], v[14:15], v[34:35] op_sel_hi:[1,0]
	v_cvt_pk_bf16_f32 v19, v16, v17
	v_cvt_pk_bf16_f32 v20, v10, v11
	v_cvt_pk_bf16_f32 v21, v12, v13
	v_pk_mul_f32 v[16:17], v[16:17], v[34:35] op_sel_hi:[1,0]
	v_pk_fma_f32 v[14:15], v[154:155], v[14:15], v[158:159]
	v_pk_mul_f32 v[12:13], v[12:13], v[34:35] op_sel_hi:[1,0]
	v_pk_mul_f32 v[10:11], v[10:11], v[34:35] op_sel_hi:[1,0]
	v_pk_fma_f32 v[16:17], v[156:157], v[16:17], v[160:161]
	v_pk_fma_f32 v[24:25], v[148:149], v[12:13], v[152:153]
	v_pk_fma_f32 v[12:13], v[146:147], v[10:11], v[150:151]
	v_cvt_pk_bf16_f32 v10, v14, v15
	v_lshlrev_b64 v[14:15], 1, v[22:23]
	v_cvt_pk_bf16_f32 v11, v16, v17
	v_cvt_pk_bf16_f32 v12, v12, v13
	v_cvt_pk_bf16_f32 v13, v24, v25
	v_lshl_add_u64 v[16:17], s[22:23], 0, v[14:15]
	global_store_dwordx4 v[16:17], v[18:21], off
	s_nop 1
	v_lshl_add_u64 v[14:15], s[24:25], 0, v[14:15]
	global_store_dwordx4 v[14:15], v[10:13], off
	s_nop 1
	v_cvt_pk_bf16_f32 v10, v6, v7
	v_cvt_pk_bf16_f32 v11, v8, v9
	v_cvt_pk_bf16_f32 v12, v2, v3
	v_cvt_pk_bf16_f32 v13, v4, v5
	v_pk_mul_f32 v[6:7], v[6:7], v[34:35] op_sel_hi:[1,0]
	v_pk_mul_f32 v[4:5], v[4:5], v[34:35] op_sel_hi:[1,0]
	v_pk_mul_f32 v[2:3], v[2:3], v[34:35] op_sel_hi:[1,0]
	v_pk_mul_f32 v[8:9], v[8:9], v[34:35] op_sel_hi:[1,0]
	v_pk_fma_f32 v[6:7], v[134:135], v[6:7], v[142:143]
	v_pk_fma_f32 v[18:19], v[132:133], v[4:5], v[140:141]
	v_pk_fma_f32 v[4:5], v[130:131], v[2:3], v[138:139]
	v_pk_fma_f32 v[8:9], v[136:137], v[8:9], v[144:145]
	v_cvt_pk_bf16_f32 v2, v6, v7
	v_lshl_add_u64 v[6:7], v[16:17], 0, s[8:9]
	v_cvt_pk_bf16_f32 v3, v8, v9
	v_cvt_pk_bf16_f32 v4, v4, v5
	v_cvt_pk_bf16_f32 v5, v18, v19
	global_store_dwordx4 v[6:7], v[10:13], off
	s_nop 1
	v_lshl_add_u64 v[6:7], v[14:15], 0, s[8:9]
	global_store_dwordx4 v[6:7], v[2:5], off
	s_nop 1

.LBB0_740:
	s_and_b64 vcc, exec, s[6:7]
	s_cbranch_vccz .LBB0_757
	s_waitcnt vmcnt(0)
	s_waitcnt lgkmcnt(0)
	s_barrier
	s_and_saveexec_b64 s[6:7], s[58:59]
	s_cbranch_execz .LBB0_756
	s_cmp_eq_u32 s100, 0
	s_cbranch_scc1 .Lwb_skip_tb3
	buffer_wbl2 sc1
	s_waitcnt vmcnt(0)
.Lwb_skip_tb3:
	v_readlane_b32 s0, v250, 13
	s_lshl_b32 s0, s0, 6
	s_ashr_i32 s1, s0, 31
	s_lshl_b64 s[0:1], s[0:1], 2
	s_mov_b64 s[10:11], exec
	s_add_u32 s0, s34, s0
	s_addc_u32 s1, s35, s1
	v_mbcnt_lo_u32_b32 v2, s10, 0
	s_add_u32 s8, s0, 0x40000
	v_mbcnt_hi_u32_b32 v2, s11, v2
	s_addc_u32 s9, s1, 0
	v_cmp_eq_u32_e32 vcc, 0, v2
	s_and_saveexec_b64 s[12:13], vcc
	s_cbranch_execz .LBB0_744
	s_bcnt1_i32_b64 s0, s[10:11]
	v_mov_b32_e32 v2, 0
	v_mov_b32_e32 v3, s0
	global_atomic_add v2, v3, s[8:9]

.LBB0_771:
	v_mul_u32_u24_e32 v246, 0x1600, v150
	s_mul_i32 s82, s36, 0x160000
	s_lshl_b32 s83, s28, 8
	v_mov_b32_e32 v240, 1.0
	s_add_u32 s86, s8, s82
	s_addc_u32 s87, s9, 0
	v_mov_b32_e32 v241, 1.0
	s_add_u32 s86, s86, s83
	s_addc_u32 s87, s87, 0
	v_lshl_add_u32 v246, v152, 1, v246
	s_cmp_eq_u32 s90, 2
	s_cselect_b32 s82, 0xb0000, 0
	s_add_u32 s86, s86, s82
	s_addc_u32 s87, s87, 0
	v_exp_f32_e64 v232, -v126
	v_exp_f32_e64 v233, -v127
	v_exp_f32_e64 v234, -v128
	v_exp_f32_e64 v235, -v129
	v_exp_f32_e64 v236, -v122
	v_exp_f32_e64 v237, -v123
	v_exp_f32_e64 v238, -v124
	v_exp_f32_e64 v239, -v125
	v_pk_add_f32 v[232:233], v[232:233], v[240:241]
	v_pk_add_f32 v[234:235], v[234:235], v[240:241]
	v_pk_add_f32 v[236:237], v[236:237], v[240:241]
	v_pk_add_f32 v[238:239], v[238:239], v[240:241]
	v_rcp_f32_e32 v232, v232
	v_rcp_f32_e32 v233, v233
	v_rcp_f32_e32 v234, v234
	v_rcp_f32_e32 v235, v235
	v_rcp_f32_e32 v236, v236
	v_rcp_f32_e32 v237, v237
	v_rcp_f32_e32 v238, v238
	v_rcp_f32_e32 v239, v239
	v_pk_mul_f32 v[118:119], v[126:127], v[118:119]
	v_pk_mul_f32 v[120:121], v[128:129], v[120:121]
	v_pk_mul_f32 v[114:115], v[122:123], v[114:115]
	v_pk_mul_f32 v[116:117], v[124:125], v[116:117]
	v_pk_mul_f32 v[118:119], v[232:233], v[118:119]
	v_pk_mul_f32 v[120:121], v[234:235], v[120:121]
	v_pk_mul_f32 v[114:115], v[236:237], v[114:115]
	v_pk_mul_f32 v[116:117], v[238:239], v[116:117]
	v_cvt_pk_bf16_f32 v242, v118, v119
	v_cvt_pk_bf16_f32 v243, v120, v121
	v_cvt_pk_bf16_f32 v244, v114, v115
	v_cvt_pk_bf16_f32 v245, v116, v117
	s_add_u32 s84, s86, 0x0
	s_addc_u32 s85, s87, 0
	global_store_dwordx4 v246, v[242:245], s[84:85]
	s_nop 1
	v_exp_f32_e64 v232, -v110
	v_exp_f32_e64 v233, -v111
	v_exp_f32_e64 v234, -v112
	v_exp_f32_e64 v235, -v113
	v_exp_f32_e64 v236, -v106
	v_exp_f32_e64 v237, -v107
	v_exp_f32_e64 v238, -v108
	v_exp_f32_e64 v239, -v109
	v_pk_add_f32 v[232:233], v[232:233], v[240:241]
	v_pk_add_f32 v[234:235], v[234:235], v[240:241]
	v_pk_add_f32 v[236:237], v[236:237], v[240:241]
	v_pk_add_f32 v[238:239], v[238:239], v[240:241]
	v_rcp_f32_e32 v232, v232
	v_rcp_f32_e32 v233, v233
	v_rcp_f32_e32 v234, v234
	v_rcp_f32_e32 v235, v235
	v_rcp_f32_e32 v236, v236
	v_rcp_f32_e32 v237, v237
	v_rcp_f32_e32 v238, v238
	v_rcp_f32_e32 v239, v239
	v_pk_mul_f32 v[102:103], v[110:111], v[102:103]
	v_pk_mul_f32 v[104:105], v[112:113], v[104:105]
	v_pk_mul_f32 v[98:99], v[106:107], v[98:99]
	v_pk_mul_f32 v[100:101], v[108:109], v[100:101]
	v_pk_mul_f32 v[102:103], v[232:233], v[102:103]
	v_pk_mul_f32 v[104:105], v[234:235], v[104:105]
	v_pk_mul_f32 v[98:99], v[236:237], v[98:99]
	v_pk_mul_f32 v[100:101], v[238:239], v[100:101]
	v_cvt_pk_bf16_f32 v242, v102, v103
	v_cvt_pk_bf16_f32 v243, v104, v105
	v_cvt_pk_bf16_f32 v244, v98, v99
	v_cvt_pk_bf16_f32 v245, v100, v101
	s_add_u32 s84, s86, 0x16000
	s_addc_u32 s85, s87, 0
	global_store_dwordx4 v246, v[242:245], s[84:85]
	s_nop 1
	v_exp_f32_e64 v232, -v94
	v_exp_f32_e64 v233, -v95
	v_exp_f32_e64 v234, -v96
	v_exp_f32_e64 v235, -v97
	v_exp_f32_e64 v236, -v90
	v_exp_f32_e64 v237, -v91
	v_exp_f32_e64 v238, -v92
	v_exp_f32_e64 v239, -v93
	v_pk_add_f32 v[232:233], v[232:233], v[240:241]
	v_pk_add_f32 v[234:235], v[234:235], v[240:241]
	v_pk_add_f32 v[236:237], v[236:237], v[240:241]
	v_pk_add_f32 v[238:239], v[238:239], v[240:241]
	v_rcp_f32_e32 v232, v232
	v_rcp_f32_e32 v233, v233
	v_rcp_f32_e32 v234, v234
	v_rcp_f32_e32 v235, v235
	v_rcp_f32_e32 v236, v236
	v_rcp_f32_e32 v237, v237
	v_rcp_f32_e32 v238, v238
	v_rcp_f32_e32 v239, v239
	v_pk_mul_f32 v[86:87], v[94:95], v[86:87]
	v_pk_mul_f32 v[88:89], v[96:97], v[88:89]
	v_pk_mul_f32 v[82:83], v[90:91], v[82:83]
	v_pk_mul_f32 v[84:85], v[92:93], v[84:85]
	v_pk_mul_f32 v[86:87], v[232:233], v[86:87]
	v_pk_mul_f32 v[88:89], v[234:235], v[88:89]
	v_pk_mul_f32 v[82:83], v[236:237], v[82:83]
	v_pk_mul_f32 v[84:85], v[238:239], v[84:85]
	v_cvt_pk_bf16_f32 v242, v86, v87
	v_cvt_pk_bf16_f32 v243, v88, v89
	v_cvt_pk_bf16_f32 v244, v82, v83
	v_cvt_pk_bf16_f32 v245, v84, v85
	s_add_u32 s84, s86, 0x2c000
	s_addc_u32 s85, s87, 0
	global_store_dwordx4 v246, v[242:245], s[84:85]
	s_nop 1
	v_exp_f32_e64 v232, -v78
	v_exp_f32_e64 v233, -v79
	v_exp_f32_e64 v234, -v80
	v_exp_f32_e64 v235, -v81
	v_exp_f32_e64 v236, -v74
	v_exp_f32_e64 v237, -v75
	v_exp_f32_e64 v238, -v76
	v_exp_f32_e64 v239, -v77
	v_pk_add_f32 v[232:233], v[232:233], v[240:241]
	v_pk_add_f32 v[234:235], v[234:235], v[240:241]
	v_pk_add_f32 v[236:237], v[236:237], v[240:241]
	v_pk_add_f32 v[238:239], v[238:239], v[240:241]
	v_rcp_f32_e32 v232, v232
	v_rcp_f32_e32 v233, v233
	v_rcp_f32_e32 v234, v234
	v_rcp_f32_e32 v235, v235
	v_rcp_f32_e32 v236, v236
	v_rcp_f32_e32 v237, v237
	v_rcp_f32_e32 v238, v238
	v_rcp_f32_e32 v239, v239
	v_pk_mul_f32 v[70:71], v[78:79], v[70:71]
	v_pk_mul_f32 v[72:73], v[80:81], v[72:73]
	v_pk_mul_f32 v[66:67], v[74:75], v[66:67]
	v_pk_mul_f32 v[68:69], v[76:77], v[68:69]
	v_pk_mul_f32 v[70:71], v[232:233], v[70:71]
	v_pk_mul_f32 v[72:73], v[234:235], v[72:73]
	v_pk_mul_f32 v[66:67], v[236:237], v[66:67]
	v_pk_mul_f32 v[68:69], v[238:239], v[68:69]
	v_cvt_pk_bf16_f32 v242, v70, v71
	v_cvt_pk_bf16_f32 v243, v72, v73
	v_cvt_pk_bf16_f32 v244, v66, v67
	v_cvt_pk_bf16_f32 v245, v68, v69
	s_add_u32 s84, s86, 0x42000
	s_addc_u32 s85, s87, 0
	global_store_dwordx4 v246, v[242:245], s[84:85]
	s_nop 1
	s_cmp_lg_u32 s90, 0
	s_cbranch_scc1 .Lht_epi_done
	v_exp_f32_e64 v232, -v62
	v_exp_f32_e64 v233, -v63
	v_exp_f32_e64 v234, -v64
	v_exp_f32_e64 v235, -v65
	v_exp_f32_e64 v236, -v58
	v_exp_f32_e64 v237, -v59
	v_exp_f32_e64 v238, -v60
	v_exp_f32_e64 v239, -v61
	v_pk_add_f32 v[232:233], v[232:233], v[240:241]
	v_pk_add_f32 v[234:235], v[234:235], v[240:241]
	v_pk_add_f32 v[236:237], v[236:237], v[240:241]
	v_pk_add_f32 v[238:239], v[238:239], v[240:241]
	v_rcp_f32_e32 v232, v232
	v_rcp_f32_e32 v233, v233
	v_rcp_f32_e32 v234, v234
	v_rcp_f32_e32 v235, v235
	v_rcp_f32_e32 v236, v236
	v_rcp_f32_e32 v237, v237
	v_rcp_f32_e32 v238, v238
	v_rcp_f32_e32 v239, v239
	v_pk_mul_f32 v[54:55], v[62:63], v[54:55]
	v_pk_mul_f32 v[56:57], v[64:65], v[56:57]
	v_pk_mul_f32 v[50:51], v[58:59], v[50:51]
	v_pk_mul_f32 v[52:53], v[60:61], v[52:53]
	v_pk_mul_f32 v[54:55], v[232:233], v[54:55]
	v_pk_mul_f32 v[56:57], v[234:235], v[56:57]
	v_pk_mul_f32 v[50:51], v[236:237], v[50:51]
	v_pk_mul_f32 v[52:53], v[238:239], v[52:53]
	v_cvt_pk_bf16_f32 v242, v54, v55
	v_cvt_pk_bf16_f32 v243, v56, v57
	v_cvt_pk_bf16_f32 v244, v50, v51
	v_cvt_pk_bf16_f32 v245, v52, v53
	s_add_u32 s84, s86, 0xb0000
	s_addc_u32 s85, s87, 0
	global_store_dwordx4 v246, v[242:245], s[84:85]
	s_nop 1
	v_exp_f32_e64 v232, -v46
	v_exp_f32_e64 v233, -v47
	v_exp_f32_e64 v234, -v48
	v_exp_f32_e64 v235, -v49
	v_exp_f32_e64 v236, -v42
	v_exp_f32_e64 v237, -v43
	v_exp_f32_e64 v238, -v44
	v_exp_f32_e64 v239, -v45
	v_pk_add_f32 v[232:233], v[232:233], v[240:241]
	v_pk_add_f32 v[234:235], v[234:235], v[240:241]
	v_pk_add_f32 v[236:237], v[236:237], v[240:241]
	v_pk_add_f32 v[238:239], v[238:239], v[240:241]
	v_rcp_f32_e32 v232, v232
	v_rcp_f32_e32 v233, v233
	v_rcp_f32_e32 v234, v234
	v_rcp_f32_e32 v235, v235
	v_rcp_f32_e32 v236, v236
	v_rcp_f32_e32 v237, v237
	v_rcp_f32_e32 v238, v238
	v_rcp_f32_e32 v239, v239
	v_pk_mul_f32 v[38:39], v[46:47], v[38:39]
	v_pk_mul_f32 v[40:41], v[48:49], v[40:41]
	v_pk_mul_f32 v[34:35], v[42:43], v[34:35]
	v_pk_mul_f32 v[36:37], v[44:45], v[36:37]
	v_pk_mul_f32 v[38:39], v[232:233], v[38:39]
	v_pk_mul_f32 v[40:41], v[234:235], v[40:41]
	v_pk_mul_f32 v[34:35], v[236:237], v[34:35]
	v_pk_mul_f32 v[36:37], v[238:239], v[36:37]
	v_cvt_pk_bf16_f32 v242, v38, v39
	v_cvt_pk_bf16_f32 v243, v40, v41
	v_cvt_pk_bf16_f32 v244, v34, v35
	v_cvt_pk_bf16_f32 v245, v36, v37
	s_add_u32 s84, s86, 0xc6000
	s_addc_u32 s85, s87, 0
	global_store_dwordx4 v246, v[242:245], s[84:85]
	s_nop 1
	v_exp_f32_e64 v232, -v30
	v_exp_f32_e64 v233, -v31
	v_exp_f32_e64 v234, -v32
	v_exp_f32_e64 v235, -v33
	v_exp_f32_e64 v236, -v26
	v_exp_f32_e64 v237, -v27
	v_exp_f32_e64 v238, -v28
	v_exp_f32_e64 v239, -v29
	v_pk_add_f32 v[232:233], v[232:233], v[240:241]
	v_pk_add_f32 v[234:235], v[234:235], v[240:241]
	v_pk_add_f32 v[236:237], v[236:237], v[240:241]
	v_pk_add_f32 v[238:239], v[238:239], v[240:241]
	v_rcp_f32_e32 v232, v232
	v_rcp_f32_e32 v233, v233
	v_rcp_f32_e32 v234, v234
	v_rcp_f32_e32 v235, v235
	v_rcp_f32_e32 v236, v236
	v_rcp_f32_e32 v237, v237
	v_rcp_f32_e32 v238, v238
	v_rcp_f32_e32 v239, v239
	v_pk_mul_f32 v[22:23], v[30:31], v[22:23]
	v_pk_mul_f32 v[24:25], v[32:33], v[24:25]
	v_pk_mul_f32 v[18:19], v[26:27], v[18:19]
	v_pk_mul_f32 v[20:21], v[28:29], v[20:21]
	v_pk_mul_f32 v[22:23], v[232:233], v[22:23]
	v_pk_mul_f32 v[24:25], v[234:235], v[24:25]
	v_pk_mul_f32 v[18:19], v[236:237], v[18:19]
	v_pk_mul_f32 v[20:21], v[238:239], v[20:21]
	v_cvt_pk_bf16_f32 v242, v22, v23
	v_cvt_pk_bf16_f32 v243, v24, v25
	v_cvt_pk_bf16_f32 v244, v18, v19
	v_cvt_pk_bf16_f32 v245, v20, v21
	s_add_u32 s84, s86, 0xdc000
	s_addc_u32 s85, s87, 0
	global_store_dwordx4 v246, v[242:245], s[84:85]
	s_nop 1
	v_exp_f32_e64 v232, -v14
	v_exp_f32_e64 v233, -v15
	v_exp_f32_e64 v234, -v16
	v_exp_f32_e64 v235, -v17
	v_exp_f32_e64 v236, -v10
	v_exp_f32_e64 v237, -v11
	v_exp_f32_e64 v238, -v12
	v_exp_f32_e64 v239, -v13
	v_pk_add_f32 v[232:233], v[232:233], v[240:241]
	v_pk_add_f32 v[234:235], v[234:235], v[240:241]
	v_pk_add_f32 v[236:237], v[236:237], v[240:241]
	v_pk_add_f32 v[238:239], v[238:239], v[240:241]
	v_rcp_f32_e32 v232, v232
	v_rcp_f32_e32 v233, v233
	v_rcp_f32_e32 v234, v234
	v_rcp_f32_e32 v235, v235
	v_rcp_f32_e32 v236, v236
	v_rcp_f32_e32 v237, v237
	v_rcp_f32_e32 v238, v238
	v_rcp_f32_e32 v239, v239
	v_pk_mul_f32 v[6:7], v[14:15], v[6:7]
	v_pk_mul_f32 v[8:9], v[16:17], v[8:9]
	v_pk_mul_f32 v[2:3], v[10:11], v[2:3]
	v_pk_mul_f32 v[4:5], v[12:13], v[4:5]
	v_pk_mul_f32 v[6:7], v[232:233], v[6:7]
	v_pk_mul_f32 v[8:9], v[234:235], v[8:9]
	v_pk_mul_f32 v[2:3], v[236:237], v[2:3]
	v_pk_mul_f32 v[4:5], v[238:239], v[4:5]
	v_cvt_pk_bf16_f32 v242, v6, v7
	v_cvt_pk_bf16_f32 v243, v8, v9
	v_cvt_pk_bf16_f32 v244, v2, v3
	v_cvt_pk_bf16_f32 v245, v4, v5
	s_add_u32 s84, s86, 0xf2000
	s_addc_u32 s85, s87, 0
	global_store_dwordx4 v246, v[242:245], s[84:85]
	s_nop 1

.LBB0_830:
	s_and_b64 vcc, exec, s[6:7]
	s_cbranch_vccz .LBB0_847
	s_waitcnt vmcnt(0)
	s_waitcnt vmcnt(0) lgkmcnt(0)
	s_barrier
	s_and_saveexec_b64 s[6:7], s[58:59]
	s_cbranch_execz .LBB0_846
	s_cmp_eq_u32 s100, 0
	s_cbranch_scc1 .Lwb_skip_tb4
	buffer_wbl2 sc1
	s_waitcnt vmcnt(0)
.Lwb_skip_tb4:
	v_readlane_b32 s0, v250, 13
	s_lshl_b32 s0, s0, 6
	s_ashr_i32 s1, s0, 31
	s_lshl_b64 s[0:1], s[0:1], 2
	s_mov_b64 s[10:11], exec
	s_add_u32 s0, s34, s0
	s_addc_u32 s1, s35, s1
	v_mbcnt_lo_u32_b32 v2, s10, 0
	s_add_u32 s0, s0, 0x40000
	v_mbcnt_hi_u32_b32 v2, s11, v2
	s_addc_u32 s1, s1, 0
	v_cmp_eq_u32_e32 vcc, 0, v2
	s_and_saveexec_b64 s[12:13], vcc
	s_cbranch_execz .LBB0_834
	s_bcnt1_i32_b64 s10, s[10:11]
	v_mov_b32_e32 v2, 0
	v_mov_b32_e32 v3, s10
	global_atomic_add v2, v3, s[0:1]
